# attention: V^T LDS tile row stride 272 and key-permuted so every PV A-fragment is one ds_read_b128 instead of a half-rate ds_read2_b64; stage 44032 B
# baseline (speedup 1.0000x reference)
; DI float bflo(unsigned u) { return __uint_as_float(u << 16); }
; DI float bfhi(unsigned u) { return __uint_as_float(u & 0xffff0000u); }
; DI f32x16 zero16() { f32x16 z; for (int i = 0; i < 16; ++i) z[i] = 0.f; return z; }
; DI void phase_attn(const Params& p, int hf, bool skipctx, char* smem, int& rot) {
;     ...
;       for (int ks = 0; ks < 6; ++ks) qu[ks] = *(const uint4*)(Qb + tq * 768 + head * 96 + ks * 16 + h * 8);
; #pragma unroll
;       for (int ks = 0; ks < 4; ++ks) {
;         const uint4 u = qu[ks];
;         qf[ks] = pack8(bflo(u.x) * QSCALE, bfhi(u.x) * QSCALE, bflo(u.y) * QSCALE, bfhi(u.y) * QSCALE, bflo(u.z) * QSCALE, bfhi(u.z) * QSCALE, bflo(u.w) * QSCALE, bfhi(u.w) * QSCALE);
;       }
;       const unsigned a1[4] = {qu[4].x, qu[4].y, qu[4].z, qu[4].w}, a2[4] = {qu[5].x, qu[5].y, qu[5].z, qu[5].w};
;       float o1[8], o2[8];
;       const int sq_ = s0 + w * 32 + r;
; #pragma unroll
;       for (int e = 0; e < 8; ++e) {
;         const float x1 = ((e & 1) ? bfhi(a1[e >> 1]) : bflo(a1[e >> 1])) * QSCALE;
;         const float x2 = ((e & 1) ? bfhi(a2[e >> 1]) : bflo(a2[e >> 1])) * QSCALE;
;         float cs = 1.f, sn = 0.f;
;         if (sq_ >= LC) { cs = axc[(sq_ - LC) * 16 + 8 * h + e]; sn = axs[(sq_ - LC) * 16 + 8 * h + e]; }
;         o1[e] = x1 * cs - x2 * sn; o2[e] = x1 * sn + x2 * cs;
;       }
;       qf[4] = pack8(o1[0], o1[1], o1[2], o1[3], o1[4], o1[5], o1[6], o1[7]);
;       qf[5] = pack8(o2[0], o2[1], o2[2], o2[3], o2[4], o2[5], o2[6], o2[7]);
;     }
;     const bf16_t* Kg = Kb + (size_t)(bl * 8 + head) * S * 96;
;     const bf16_t* Vg = VTb + (size_t)(bl * 8 + head) * 64 * S;
;     f32x16 o[2]; o[0] = zero16(); o[1] = zero16();
;     float m_run = -1e30f, l_run = 0.f;
;     uint4 ak0, ak1, ak2, av0, av1, bk0, bk1, bk2, bv0, bv1;
;     const int kr0 = tid / 12, kc0 = tid - kr0 * 12, kr1 = (tid + 512) / 12, kc1 = (tid + 512) - kr1 * 12, kr2 = (tid + 1024) / 12, kc2 = (tid + 1024) - kr2 * 12;
;     const int vr0 = tid >> 4, vr1 = (tid + 512) >> 4, vc = tid & 15;
.LBB0_794:
	s_or_b64 exec, exec, s[26:27]
	s_waitcnt vmcnt(0)
	v_lshlrev_b32_e32 v27, 16, v23
	v_lshlrev_b32_e32 v26, 16, v19
	v_pk_mul_f32 v[26:27], v[26:27], s[48:49] op_sel_hi:[1,0]
	v_lshlrev_b32_e32 v47, 16, v22
	v_pk_mul_f32 v[28:29], v[26:27], v[30:31] op_sel:[0,1] op_sel_hi:[1,0]
	v_pk_mul_f32 v[26:27], v[26:27], v[30:31]
	v_and_b32_e32 v30, 0xffff0000, v19
	v_lshlrev_b32_e32 v46, 16, v18
	v_and_b32_e32 v19, 0xffff0000, v22
	v_and_b32_e32 v18, 0xffff0000, v18
	v_and_b32_e32 v31, 0xffff0000, v23
	v_pk_mul_f32 v[46:47], v[46:47], s[48:49] op_sel_hi:[1,0]
	v_pk_mul_f32 v[22:23], v[18:19], s[48:49] op_sel_hi:[1,0]
	v_pk_mul_f32 v[48:49], v[46:47], v[42:43] op_sel:[0,1] op_sel_hi:[1,0]
	v_pk_mul_f32 v[42:43], v[46:47], v[42:43]
	v_pk_mul_f32 v[18:19], v[22:23], v[40:41] op_sel:[0,1] op_sel_hi:[1,0]
	v_pk_mul_f32 v[22:23], v[22:23], v[40:41]
	v_mov_b32_e32 v40, v42
	v_mov_b32_e32 v41, v22
	v_mov_b32_e32 v22, v43
	v_pk_add_f32 v[22:23], v[40:41], v[22:23]
	v_lshlrev_b32_e32 v41, 16, v21
	v_lshlrev_b32_e32 v40, 16, v17
	v_pk_mul_f32 v[40:41], v[40:41], s[48:49] op_sel_hi:[1,0]
	v_mov_b32_e32 v46, v48
	v_mov_b32_e32 v47, v18
	v_mov_b32_e32 v18, v49
	v_pk_mul_f32 v[42:43], v[40:41], v[32:33] op_sel:[0,1] op_sel_hi:[1,0]
	v_pk_mul_f32 v[40:41], v[40:41], v[32:33]
	v_and_b32_e32 v33, 0xffff0000, v21
	v_and_b32_e32 v32, 0xffff0000, v17
	v_pk_add_f32 v[18:19], v[46:47], v[18:19] neg_lo:[0,1] neg_hi:[0,1]
	v_pk_mul_f32 v[46:47], v[32:33], s[48:49] op_sel_hi:[1,0]
	v_mov_b32_e32 v48, v42
	v_pk_mul_f32 v[32:33], v[46:47], v[34:35] op_sel:[0,1] op_sel_hi:[1,0]
	v_pk_mul_f32 v[34:35], v[46:47], v[34:35]
	v_mov_b32_e32 v49, v32
	v_mov_b32_e32 v32, v43
	v_mov_b32_e32 v42, v40
	v_mov_b32_e32 v43, v34
	v_mov_b32_e32 v34, v41
	v_lshlrev_b32_e32 v41, 16, v20
	v_lshlrev_b32_e32 v40, 16, v16
	v_and_b32_e32 v17, 0xffff0000, v20
	v_and_b32_e32 v16, 0xffff0000, v16
	v_pk_mul_f32 v[40:41], v[40:41], s[48:49] op_sel_hi:[1,0]
	v_pk_mul_f32 v[20:21], v[16:17], s[48:49] op_sel_hi:[1,0]
	v_pk_add_f32 v[34:35], v[42:43], v[34:35]
	v_pk_mul_f32 v[42:43], v[40:41], v[38:39] op_sel:[0,1] op_sel_hi:[1,0]
	v_pk_mul_f32 v[38:39], v[40:41], v[38:39]
	v_pk_mul_f32 v[16:17], v[20:21], v[36:37] op_sel:[0,1] op_sel_hi:[1,0]
	v_pk_mul_f32 v[20:21], v[20:21], v[36:37]
	v_mov_b32_e32 v36, v38
	v_mov_b32_e32 v37, v20
	v_mov_b32_e32 v20, v39
	v_pk_add_f32 v[20:21], v[36:37], v[20:21]
	v_lshlrev_b32_e32 v36, 16, v12
	v_and_b32_e32 v37, 0xffff0000, v12
	v_lshlrev_b32_e32 v12, 16, v13
	v_and_b32_e32 v13, 0xffff0000, v13
	v_pk_mul_f32 v[12:13], v[12:13], s[48:49] op_sel_hi:[1,0]
	v_lshlrev_b32_e32 v38, 16, v14
	v_cvt_pk_bf16_f32 v65, v12, v13
	v_lshlrev_b32_e32 v12, 16, v8
	v_and_b32_e32 v13, 0xffff0000, v8
	v_lshlrev_b32_e32 v8, 16, v9
	v_and_b32_e32 v9, 0xffff0000, v9
	v_pk_mul_f32 v[8:9], v[8:9], s[48:49] op_sel_hi:[1,0]
	v_and_b32_e32 v39, 0xffff0000, v14
	v_cvt_pk_bf16_f32 v69, v8, v9
	v_lshlrev_b32_e32 v8, 16, v4
	v_and_b32_e32 v9, 0xffff0000, v4
	v_lshlrev_b32_e32 v4, 16, v5
	v_and_b32_e32 v5, 0xffff0000, v5
	v_lshlrev_b32_e32 v14, 16, v15
	v_and_b32_e32 v15, 0xffff0000, v15
	v_pk_mul_f32 v[4:5], v[4:5], s[48:49] op_sel_hi:[1,0]
	s_mov_b32 s16, 0x2aaaaaab
	v_pk_mul_f32 v[14:15], v[14:15], s[48:49] op_sel_hi:[1,0]
	v_cvt_pk_bf16_f32 v73, v4, v5
	v_mul_hi_i32 v4, v160, s16
	v_cvt_pk_bf16_f32 v67, v14, v15
	v_lshlrev_b32_e32 v14, 16, v10
	v_and_b32_e32 v15, 0xffff0000, v10
	v_lshlrev_b32_e32 v10, 16, v11
	v_and_b32_e32 v11, 0xffff0000, v11
	v_lshrrev_b32_e32 v5, 31, v4
	v_ashrrev_i32_e32 v4, 1, v4
	v_pk_mul_f32 v[10:11], v[10:11], s[48:49] op_sel_hi:[1,0]
	v_add_u32_e32 v45, v4, v5
	v_cvt_pk_bf16_f32 v71, v10, v11
	v_lshlrev_b32_e32 v10, 16, v6
	v_and_b32_e32 v11, 0xffff0000, v6
	v_lshlrev_b32_e32 v6, 16, v7
	v_and_b32_e32 v7, 0xffff0000, v7
	v_mad_u64_u32 v[4:5], s[38:39], v45, -12, v[160:161]
	v_add_u32_e32 v164, 0x200, v160
	v_pk_mul_f32 v[6:7], v[6:7], s[48:49] op_sel_hi:[1,0]
	v_mul_hi_i32 v5, v164, s16
	v_cvt_pk_bf16_f32 v75, v6, v7
	v_lshrrev_b32_e32 v6, 31, v5
	v_ashrrev_i32_e32 v5, 1, v5
	s_mul_i32 s15, s4, 0xcc000
	v_add_u32_e32 v5, v5, v6
	v_pk_mul_f32 v[38:39], v[38:39], s[48:49] op_sel_hi:[1,0]
	v_pk_mul_f32 v[14:15], v[14:15], s[48:49] op_sel_hi:[1,0]
	s_mul_hi_i32 s5, s4, 0xcc000
	s_add_u32 s26, s90, s15
	v_mad_u64_u32 v[6:7], s[38:39], v5, -12, v[164:165]
	v_add_u32_e32 v162, 0x400, v160
	v_cvt_pk_bf16_f32 v66, v38, v39
	v_cvt_pk_bf16_f32 v70, v14, v15
	v_pk_mul_f32 v[8:9], v[8:9], s[48:49] op_sel_hi:[1,0]
	v_pk_mul_f32 v[10:11], v[10:11], s[48:49] op_sel_hi:[1,0]
	s_addc_u32 s27, s91, s5
	v_mul_hi_i32 v7, v162, s16
	v_lshlrev_b32_e32 v14, 3, v4
	v_lshlrev_b32_e32 v38, 3, v6
	v_pk_mul_f32 v[36:37], v[36:37], s[48:49] op_sel_hi:[1,0]
	v_pk_mul_f32 v[12:13], v[12:13], s[48:49] op_sel_hi:[1,0]
	v_cvt_pk_bf16_f32 v72, v8, v9
	v_cvt_pk_bf16_f32 v74, v10, v11
	v_lshrrev_b32_e32 v8, 31, v7
	v_ashrrev_i32_e32 v7, 1, v7
	v_mov_b64_e32 v[10:11], s[26:27]
	v_ashrrev_i32_e32 v15, 31, v14
	v_ashrrev_i32_e32 v39, 31, v38
	v_cvt_pk_bf16_f32 v64, v36, v37
	v_cvt_pk_bf16_f32 v68, v12, v13
	v_add_u32_e32 v7, v7, v8
	v_mad_i64_i32 v[12:13], s[26:27], v45, s17, v[10:11]
	v_lshlrev_b64 v[14:15], 1, v[14:15]
	v_mad_i64_i32 v[36:37], s[26:27], v5, s17, v[10:11]
	v_lshlrev_b64 v[38:39], 1, v[38:39]
	v_mad_u64_u32 v[8:9], s[38:39], v7, -12, v[162:163]
	v_lshl_add_u64 v[12:13], v[12:13], 0, v[14:15]
	v_lshl_add_u64 v[36:37], v[36:37], 0, v[38:39]
	s_barrier
; DI f32x16 zero16() { f32x16 z; for (int i = 0; i < 16; ++i) z[i] = 0.f; return z; }
; DI void phase_attn(const Params& p, int hf, bool skipctx, char* smem, int& rot) {
;     ...
;     const bf16_t* Kg = Kb + (size_t)(bl * 8 + head) * S * 96;
;     const bf16_t* Vg = VTb + (size_t)(bl * 8 + head) * 64 * S;
;     f32x16 o[2]; o[0] = zero16(); o[1] = zero16();
;     float m_run = -1e30f, l_run = 0.f;
;     uint4 ak0, ak1, ak2, av0, av1, bk0, bk1, bk2, bv0, bv1;
;     const int kr0 = tid / 12, kc0 = tid - kr0 * 12, kr1 = (tid + 512) / 12, kc1 = (tid + 512) - kr1 * 12, kr2 = (tid + 1024) / 12, kc2 = (tid + 1024) - kr2 * 12;
;     const int vr0 = tid >> 4, vr1 = (tid + 512) >> 4, vc = tid & 15;
;     ...
;     __syncthreads();
;     ATT_LOAD(ak0, ak1, ak2, av0, av1, 0);
;     ATT_LOAD(bk0, bk1, bk2, bv0, bv1, 1);
	global_load_dwordx4 v[76:79], v[12:13], off
	global_load_dwordx4 v[80:83], v[36:37], off
	v_lshlrev_b32_e32 v36, 3, v8
	s_mul_i32 s15, s4, 0x88000
	v_readlane_b32 s36, v252, 5
	v_ashrrev_i32_e32 v37, 31, v36
	s_mul_hi_i32 s5, s4, 0x88000
	v_readlane_b32 s37, v252, 6
	s_add_u32 s36, s36, s15
	v_mad_i64_i32 v[12:13], s[26:27], v7, s17, v[10:11]
	v_lshlrev_b64 v[36:37], 1, v[36:37]
	s_addc_u32 s37, s37, s5
	v_lshl_add_u64 v[12:13], v[12:13], 0, v[36:37]
	v_mov_b32_e32 v40, v42
	v_mov_b32_e32 v41, v16
	v_mov_b32_e32 v16, v43
	v_ashrrev_i32_e32 v9, 4, v160
	v_ashrrev_i32_e32 v50, 4, v164
	global_load_dwordx4 v[84:87], v[12:13], off
	v_mov_b64_e32 v[12:13], s[36:37]
	s_movk_i32 s16, 0x2200
	v_lshlrev_b32_e32 v165, 4, v160
	v_cvt_pk_bf16_f32 v100, v20, v21
	v_add_u32_e32 v20, 0x80, v5
	v_pk_add_f32 v[16:17], v[40:41], v[16:17] neg_lo:[0,1] neg_hi:[0,1]
	v_mad_i64_i32 v[40:41], s[26:27], v9, s16, v[12:13]
	v_and_b32_e32 v42, 0xf0, v165
	v_mov_b32_e32 v43, v221
	v_mad_i64_i32 v[12:13], s[26:27], v50, s16, v[12:13]
	v_cvt_pk_bf16_f32 v98, v18, v19
	v_cvt_pk_bf16_f32 v102, v22, v23
	v_add_u32_e32 v18, 0x80, v45
	v_mad_i64_i32 v[20:21], s[26:27], v20, s17, v[10:11]
	v_add_u32_e32 v22, 0x80, v7
	v_lshl_add_u64 v[40:41], v[40:41], 0, v[42:43]
	v_lshl_add_u64 v[12:13], v[12:13], 0, v[42:43]
	v_mad_i64_i32 v[18:19], s[26:27], v18, s17, v[10:11]
	v_lshl_add_u64 v[20:21], v[20:21], 0, v[38:39]
	v_mad_i64_i32 v[10:11], s[26:27], v22, s17, v[10:11]
	global_load_dwordx4 v[92:95], v[40:41], off
	global_load_dwordx4 v[104:107], v[12:13], off
	v_lshl_add_u64 v[18:19], v[18:19], 0, v[14:15]
	v_lshl_add_u64 v[10:11], v[10:11], 0, v[36:37]
	global_load_dwordx4 v[108:111], v[20:21], off
	global_load_dwordx4 v[116:119], v[10:11], off
	global_load_dwordx4 v[120:123], v[40:41], off offset:256
	global_load_dwordx4 v[112:115], v[18:19], off
	global_load_dwordx4 v[124:127], v[12:13], off offset:256
	v_lshlrev_b32_e32 v46, 16, v0
	v_and_b32_e32 v47, 0xffff0000, v0
	v_lshlrev_b32_e32 v0, 16, v1
	v_and_b32_e32 v1, 0xffff0000, v1
	v_pk_mul_f32 v[30:31], v[30:31], s[48:49] op_sel_hi:[1,0]
	v_pk_add_f32 v[32:33], v[48:49], v[32:33] neg_lo:[0,1] neg_hi:[0,1]
	v_pk_mul_f32 v[0:1], v[0:1], s[48:49] op_sel_hi:[1,0]
	v_lshlrev_b32_e32 v48, 16, v2
	v_and_b32_e32 v49, 0xffff0000, v2
	v_lshlrev_b32_e32 v2, 16, v3
	v_and_b32_e32 v3, 0xffff0000, v3
	v_pk_mul_f32 v[2:3], v[2:3], s[48:49] op_sel_hi:[1,0]
	v_cvt_pk_bf16_f32 v89, v0, v1
	v_pk_mul_f32 v[0:1], v[30:31], v[24:25] op_sel:[0,1] op_sel_hi:[1,0]
	v_cvt_pk_bf16_f32 v91, v2, v3
	v_mov_b32_e32 v2, v28
	v_mov_b32_e32 v3, v0
	v_mov_b32_e32 v0, v29
	v_pk_add_f32 v[0:1], v[2:3], v[0:1] neg_lo:[0,1] neg_hi:[0,1]
	v_pk_mul_f32 v[2:3], v[30:31], v[24:25]
	v_mul_lo_u32 v10, v45, s97
	v_mov_b32_e32 v24, v26
	v_mov_b32_e32 v25, v2
	v_mov_b32_e32 v2, v27
	v_add_u32_e32 v10, 0, v10
	v_lshlrev_b32_e32 v4, 4, v4
	v_pk_add_f32 v[2:3], v[24:25], v[2:3]
	v_add_u32_e32 v176, v10, v4
	v_mul_lo_u32 v4, v5, s97
	v_cvt_pk_bf16_f32 v103, v2, v3
	v_mad_i64_i32 v[2:3], s[26:27], v5, s17, 0
	v_add_u32_e32 v4, 0, v4
	v_lshlrev_b32_e32 v5, 4, v6
	v_add_u32_e32 v177, v4, v5
	v_mul_lo_u32 v4, v7, s97
	v_add_u32_e32 v4, 0, v4
	v_lshlrev_b32_e32 v5, 4, v8
	s_movk_i32 s20, 0x108
	v_cvt_pk_bf16_f32 v96, v16, v17
	v_cvt_pk_bf16_f32 v99, v0, v1
	v_mad_i64_i32 v[0:1], s[26:27], v45, s17, 0
	v_mad_i64_i32 v[16:17], s[26:27], v7, s17, 0
	v_add_u32_e32 v178, v4, v5
	v_mul_lo_u32 v4, v9, s20
	v_add_u32_e32 v5, 0, v4
	s_movk_i32 s26, 0x6800
	v_add3_u32 v179, v5, v42, s26
	v_mul_lo_u32 v5, v50, s20
	v_add_u32_e32 v6, 0, v5
	v_add3_u32 v180, v6, v42, s26
	v_or_b32_e32 v181, 32, v161
	v_or_b32_e32 v182, 64, v161
	v_or_b32_e32 v183, 0x60, v161
	v_readlane_b32 s26, v254, 35
	v_mul_u32_u24_e32 v19, 0x108, v44
	v_mad_u32_u24 v18, v44, s97, 0
	v_add_u32_e32 v21, s26, v4
	v_add_u32_e32 v22, s26, v5
	v_add_u32_e32 v23, s26, v161
	v_add_u32_e32 v24, s26, v181
	v_mov_b32_e32 v4, s26
	v_add_u32_e32 v25, s26, v182
	v_add_u32_e32 v26, s26, v183
	v_readlane_b32 s26, v254, 36
	v_mad_u32_u24 v184, v44, s20, v4
	v_add_u32_e32 v20, 0, v161
	v_add_u32_e32 v27, s26, v161
	v_add_u32_e32 v28, s26, v181
	v_mov_b32_e32 v4, s26
	v_add_u32_e32 v29, s26, v182
	v_add_u32_e32 v30, s26, v183
	s_add_u32 s26, s15, 0x1a49c300
	s_addc_u32 s27, s5, 0
	v_mad_u32_u24 v185, v44, s20, v4
	v_mov_b64_e32 v[4:5], s[26:27]
	v_mad_i64_i32 v[166:167], s[26:27], v9, s16, v[4:5]
	v_mad_i64_i32 v[168:169], s[26:27], v50, s16, v[4:5]
	v_mad_i64_i32 v[4:5], s[26:27], s4, v231, v[16:17]
	v_mad_i64_i32 v[2:3], s[26:27], s4, v231, v[2:3]
	v_mad_i64_i32 v[0:1], s[4:5], s4, v231, v[0:1]
	v_lshl_add_u64 v[174:175], v[0:1], 0, v[14:15]
	v_mov_b32_e32 v14, v221
	v_mov_b32_e32 v15, v221
	v_add_u32_e32 v186, v21, v42
	v_add_u32_e32 v187, v22, v42
	v_add_u32_e32 v188, v23, v19
	v_add_u32_e32 v16, v24, v19
	v_add_u32_e32 v17, v25, v19
	v_add_u32_e32 v21, v26, v19
	v_add_u32_e32 v22, v28, v19
	v_add_u32_e32 v23, v29, v19
	v_add_u32_e32 v24, v30, v19
	v_pk_mul_f32 v[46:47], v[46:47], s[48:49] op_sel_hi:[1,0]
	v_pk_mul_f32 v[48:49], v[48:49], s[48:49] op_sel_hi:[1,0]
	v_lshl_add_u64 v[170:171], v[4:5], 0, v[36:37]
	v_lshl_add_u64 v[172:173], v[2:3], 0, v[38:39]
	v_mov_b32_e32 v0, v221
	v_mov_b32_e32 v1, v221
	v_mov_b32_e32 v2, v221
	v_mov_b32_e32 v3, v221
	v_mov_b32_e32 v4, v221
	v_mov_b32_e32 v5, v221
	v_mov_b32_e32 v6, v221
	v_mov_b32_e32 v7, v221
	v_mov_b32_e32 v8, v221
	v_mov_b32_e32 v9, v221
	v_mov_b32_e32 v10, v221
	v_mov_b32_e32 v11, v221
	v_mov_b32_e32 v12, v221
	v_mov_b32_e32 v13, v221
	v_add_u32_e32 v189, v27, v19
	v_add_u32_e32 v190, v18, v220
	v_add_u32_e32 v191, v20, v19
	v_add_u32_e32 v194, 0x2000, v16
	v_add_u32_e32 v204, 0x2000, v17
	v_add_u32_e32 v206, 0x2000, v21
	v_add_u32_e32 v208, 0x2000, v22
	v_add_u32_e32 v210, 0x2000, v23
	v_add_u32_e32 v211, 0x2000, v24
	v_mov_b64_e32 v[30:31], v[14:15]
	v_cvt_pk_bf16_f32 v88, v46, v47
	v_cvt_pk_bf16_f32 v90, v48, v49
	v_cvt_pk_bf16_f32 v97, v32, v33
	v_cvt_pk_bf16_f32 v101, v34, v35
	v_or_b32_e32 v166, v166, v42
	v_or_b32_e32 v168, v168, v42
	s_mov_b32 s4, 0
	v_mov_b32_e32 v212, 0xf149f2ca
	v_mov_b32_e32 v213, 0
	v_mov_b64_e32 v[28:29], v[12:13]
	v_mov_b64_e32 v[26:27], v[10:11]
	v_mov_b64_e32 v[24:25], v[8:9]
	v_mov_b64_e32 v[22:23], v[6:7]
	v_mov_b64_e32 v[20:21], v[4:5]
	v_mov_b64_e32 v[18:19], v[2:3]
	v_mov_b64_e32 v[16:17], v[0:1]
	v_and_b32_e32 v200, 15, v192
	v_lshrrev_b32_e32 v201, 4, v192
	v_mul_u32_u24_e32 v179, 0x110, v201
	v_lshrrev_b32_e32 v202, 1, v200
	v_lshl_add_u32 v179, v202, 5, v179
	v_and_b32_e32 v202, 1, v200
	v_lshl_add_u32 v179, v202, 3, v179
	v_add_u32_e32 v179, 0x6800, v179
	v_add_u32_e32 v180, 0x2200, v179
	v_add_u32_e32 v186, 0xac00, v179
	v_add_u32_e32 v187, 0xac00, v180
	v_and_b32_e32 v200, 31, v192
	v_bfe_u32 v201, v192, 5, 1
	v_mul_u32_u24_e32 v191, 0x110, v200
	v_lshl_add_u32 v191, v201, 4, v191
	v_add_u32_e32 v191, 0x6800, v191
	s_waitcnt vmcnt(9)
; DI void phase_attn(const Params& p, int hf, bool skipctx, char* smem, int& rot) {
;     ...
;     ATT_WRITE(ak0, ak1, ak2, av0, av1, 0);
;     __syncthreads();
	ds_write_b128 v176, v[76:79]
	s_waitcnt vmcnt(8)
	ds_write_b128 v177, v[80:83]
	s_waitcnt vmcnt(7)
	ds_write_b128 v178, v[84:87]
	s_waitcnt vmcnt(6)
	ds_write2_b64 v179, v[92:93], v[94:95] offset1:2
	s_waitcnt vmcnt(5)
	ds_write2_b64 v180, v[104:105], v[106:107] offset1:2
	s_waitcnt lgkmcnt(0)
	s_barrier

; #define MFMA(a, b, c) __builtin_amdgcn_mfma_f32_32x32x16_bf16((a), (b), (c), 0, 0, 0)
; DI float fexp2(float x) { return __builtin_amdgcn_exp2f(x); }
; DI f32x16 zero16() { f32x16 z; for (int i = 0; i < 16; ++i) z[i] = 0.f; return z; }
; DI void phase_attn(const Params& p, int hf, bool skipctx, char* smem, int& rot) {
;     ...
;     auto compute = [&](int buf, int half) {
;       const char* sk = smem + buf * STG + half * 64 * KROW; const char* sv = smem + buf * STG + KB_ + half * 128;
;       f32x16 st[2]; st[0] = zero16(); st[1] = zero16();
;       {
;         bf16x8 kf[2][6];
; #pragma unroll
;         for (int kb = 0; kb < 2; ++kb)
; #pragma unroll
;           for (int ks = 0; ks < 6; ++ks) kf[kb][ks] = *(const bf16x8*)(sk + (kb * 32 + r) * KROW + (ks * 16 + h * 8) * 2);
;         __builtin_amdgcn_sched_barrier(0);
; #pragma unroll
;         for (int ks = 0; ks < 6; ++ks)
; #pragma unroll
;           for (int kb = 0; kb < 2; ++kb) st[kb] = MFMA(kf[kb][ks], qf[ks], st[kb]);
;         __builtin_amdgcn_sched_barrier(0);
;       }
;       bf16x8 vf[2][2][2];
; #pragma unroll
;       for (int kb = 0; kb < 2; ++kb)
; #pragma unroll
;         for (int s2 = 0; s2 < 2; ++s2)
; #pragma unroll
;           for (int dvb = 0; dvb < 2; ++dvb) {
;             const char* vp = sv + (dvb * 32 + r) * VROW + (kb * 32 + 16 * s2 + 4 * h) * 2;
;             const s16x4 lo = *(const s16x4*)vp, hi = *(const s16x4*)(vp + 16);
;             vf[kb][s2][dvb] = __builtin_shufflevector(lo, hi, 0, 1, 2, 3, 4, 5, 6, 7);
;           }
;       float mx = st[0][0];
; #pragma unroll
;       for (int i = 0; i < 16; ++i) { mx = fmaxf(mx, st[0][i]); mx = fmaxf(mx, st[1][i]); }
;       if (__any(mx > m_run + 8.f)) {
;         mx = fmaxf(mx, __shfl_xor(mx, 32));
;         const float m_new = fmaxf(m_run, mx);
;         const float alpha = fexp2(m_run - m_new);
;         m_run = m_new;
;         l_run *= alpha;
; #pragma unroll
;         for (int i = 0; i < 16; ++i) { o[0][i] *= alpha; o[1][i] *= alpha; }
;       }
;       float ps = 0.f;
; #pragma unroll
;       for (int kb = 0; kb < 2; ++kb)
; #pragma unroll
;         for (int i = 0; i < 16; ++i) { const float e = fexp2(st[kb][i] - m_run); st[kb][i] = e; ps += e; }
.LBB0_797:
	s_waitcnt lgkmcnt(11)
	v_mfma_f32_32x32x16_bf16 v[48:63], v[32:35], v[64:67], 0
	s_waitcnt lgkmcnt(5)
	v_mfma_f32_32x32x16_bf16 v[32:47], v[36:39], v[64:67], 0
	v_mfma_f32_32x32x16_bf16 v[48:63], v[128:131], v[68:71], v[48:63]
	s_waitcnt lgkmcnt(4)
	v_mfma_f32_32x32x16_bf16 v[32:47], v[148:151], v[68:71], v[32:47]
	v_mfma_f32_32x32x16_bf16 v[48:63], v[132:135], v[72:75], v[48:63]
	s_waitcnt lgkmcnt(3)
	v_mfma_f32_32x32x16_bf16 v[32:47], v[152:155], v[72:75], v[32:47]
	v_mfma_f32_32x32x16_bf16 v[48:63], v[136:139], v[88:91], v[48:63]
	s_waitcnt lgkmcnt(2)
	v_mfma_f32_32x32x16_bf16 v[32:47], v[156:159], v[88:91], v[32:47]
	v_mfma_f32_32x32x16_bf16 v[48:63], v[140:143], v[96:99], v[48:63]
	s_waitcnt lgkmcnt(1)
	v_mfma_f32_32x32x16_bf16 v[32:47], v[214:217], v[96:99], v[32:47]
	v_mfma_f32_32x32x16_bf16 v[48:63], v[144:147], v[100:103], v[48:63]
	s_waitcnt lgkmcnt(0)
	v_mfma_f32_32x32x16_bf16 v[32:47], v[234:237], v[100:103], v[32:47]
	s_nop 3
	ds_read_b128 v[156:159], v191 offset:0
	ds_read_b128 v[148:151], v191 offset:32
	ds_read_b128 v[152:155], v191 offset:8704
	ds_read_b128 v[144:147], v191 offset:8736
	ds_read_b128 v[140:143], v191 offset:64
	ds_read_b128 v[136:139], v191 offset:8768
	ds_read_b128 v[132:135], v191 offset:96
	ds_read_b128 v[128:131], v191 offset:8800
	v_max_f32_e32 v195, v32, v32
	v_max_f32_e32 v200, v48, v48
	v_max_f32_e32 v195, v200, v195
	v_max3_f32 v195, v195, v49, v33
	v_max3_f32 v195, v195, v50, v34
	v_max3_f32 v195, v195, v51, v35
	v_max3_f32 v195, v195, v52, v36
	v_max3_f32 v195, v195, v53, v37
	v_max3_f32 v195, v195, v54, v38
	v_max3_f32 v195, v195, v55, v39
	v_max3_f32 v195, v195, v56, v40
	v_max3_f32 v195, v195, v57, v41
	v_max3_f32 v195, v195, v58, v42
	v_max3_f32 v195, v195, v59, v43
	v_max3_f32 v195, v195, v60, v44
	v_max3_f32 v195, v195, v61, v45
	v_max3_f32 v195, v195, v62, v46
	v_max3_f32 v217, v195, v63, v47
	v_add_f32_e32 v216, 0x41000000, v212
	v_cmp_gt_f32_e32 vcc, v217, v216
	s_cbranch_vccz .LBB0_799
	v_cmp_lt_i32_e32 vcc, v224, v207
	s_nop 1
	v_cndmask_b32_e32 v195, v205, v224, vcc
	v_lshlrev_b32_e32 v195, 2, v195
	ds_bpermute_b32 v195, v195, v217
	s_waitcnt lgkmcnt(0)
	v_max3_f32 v195, v212, v217, v195
	v_sub_f32_e32 v200, v212, v195
	v_exp_f32_e32 v200, v200
	v_add_f32_e32 v216, 0x41000000, v195
	v_mov_b32_e32 v212, v195
	v_mul_f32_e32 v213, v213, v200
	v_pk_mul_f32 v[30:31], v[30:31], v[200:201] op_sel_hi:[1,0]
	v_pk_mul_f32 v[28:29], v[28:29], v[200:201] op_sel_hi:[1,0]
	v_pk_mul_f32 v[26:27], v[26:27], v[200:201] op_sel_hi:[1,0]
	v_pk_mul_f32 v[24:25], v[24:25], v[200:201] op_sel_hi:[1,0]
	v_pk_mul_f32 v[22:23], v[22:23], v[200:201] op_sel_hi:[1,0]
	v_pk_mul_f32 v[20:21], v[20:21], v[200:201] op_sel_hi:[1,0]
	v_pk_mul_f32 v[18:19], v[18:19], v[200:201] op_sel_hi:[1,0]
	v_pk_mul_f32 v[16:17], v[16:17], v[200:201] op_sel_hi:[1,0]
	v_pk_mul_f32 v[14:15], v[14:15], v[200:201] op_sel_hi:[1,0]
	v_pk_mul_f32 v[12:13], v[12:13], v[200:201] op_sel_hi:[1,0]
	v_pk_mul_f32 v[10:11], v[10:11], v[200:201] op_sel_hi:[1,0]
	v_pk_mul_f32 v[8:9], v[8:9], v[200:201] op_sel_hi:[1,0]
	v_pk_mul_f32 v[6:7], v[6:7], v[200:201] op_sel_hi:[1,0]
	v_pk_mul_f32 v[4:5], v[4:5], v[200:201] op_sel_hi:[1,0]
	v_pk_mul_f32 v[2:3], v[2:3], v[200:201] op_sel_hi:[1,0]
	v_pk_mul_f32 v[0:1], v[0:1], v[200:201] op_sel_hi:[1,0]
.LBB0_799:
	v_sub_f32_e32 v48, v48, v212
	v_exp_f32_e32 v48, v48
	v_sub_f32_e32 v49, v49, v212
	v_exp_f32_e32 v49, v49
	v_sub_f32_e32 v50, v50, v212
	v_exp_f32_e32 v50, v50
	v_sub_f32_e32 v51, v51, v212
	v_exp_f32_e32 v51, v51
	v_sub_f32_e32 v52, v52, v212
	v_add_f32_e32 v195, 0, v48
	v_exp_f32_e32 v52, v52
	v_sub_f32_e32 v53, v53, v212
	v_add_f32_e32 v195, v49, v195
	v_exp_f32_e32 v53, v53
	v_sub_f32_e32 v54, v54, v212
	v_add_f32_e32 v195, v50, v195
	v_exp_f32_e32 v54, v54
	v_sub_f32_e32 v55, v55, v212
	v_add_f32_e32 v195, v51, v195
	v_exp_f32_e32 v55, v55
	v_sub_f32_e32 v56, v56, v212
	v_add_f32_e32 v195, v52, v195
	v_exp_f32_e32 v56, v56
	v_sub_f32_e32 v57, v57, v212
	v_add_f32_e32 v195, v53, v195
	v_exp_f32_e32 v57, v57
	v_sub_f32_e32 v58, v58, v212
	v_add_f32_e32 v195, v54, v195
	v_exp_f32_e32 v58, v58
	v_sub_f32_e32 v59, v59, v212
	v_add_f32_e32 v195, v55, v195
	v_exp_f32_e32 v59, v59
	v_sub_f32_e32 v60, v60, v212
	v_add_f32_e32 v195, v56, v195
	v_exp_f32_e32 v60, v60
	v_sub_f32_e32 v61, v61, v212
	v_add_f32_e32 v195, v57, v195
	v_exp_f32_e32 v61, v61
	v_sub_f32_e32 v62, v62, v212
	v_add_f32_e32 v195, v58, v195
	v_exp_f32_e32 v62, v62
	v_sub_f32_e32 v63, v63, v212
	v_add_f32_e32 v195, v59, v195
	v_exp_f32_e32 v63, v63
	v_sub_f32_e32 v32, v32, v212
	v_add_f32_e32 v195, v60, v195
	v_exp_f32_e32 v200, v32
	v_sub_f32_e32 v32, v33, v212
	v_add_f32_e32 v195, v61, v195
	v_exp_f32_e32 v201, v32
	v_sub_f32_e32 v33, v34, v212
	v_add_f32_e32 v32, v62, v195
	v_exp_f32_e32 v195, v33
	v_sub_f32_e32 v33, v35, v212
	v_add_f32_e32 v32, v63, v32
	v_exp_f32_e32 v202, v33
	v_sub_f32_e32 v33, v36, v212
	v_add_f32_e32 v32, v200, v32
	v_exp_f32_e32 v36, v33
	v_sub_f32_e32 v33, v37, v212
	v_add_f32_e32 v32, v201, v32
	v_exp_f32_e32 v37, v33
	v_add_f32_e32 v32, v195, v32
	v_add_f32_e32 v32, v202, v32
	v_add_f32_e32 v32, v36, v32
	v_add_f32_e32 v203, v37, v32
	v_cvt_pk_bf16_f32 v32, v48, v49
	v_cvt_pk_bf16_f32 v33, v50, v51
	v_cvt_pk_bf16_f32 v34, v52, v53
	v_cvt_pk_bf16_f32 v35, v54, v55
	v_sub_f32_e32 v38, v38, v212
	v_exp_f32_e32 v38, v38
	s_waitcnt lgkmcnt(7)
	v_mfma_f32_32x32x16_bf16 v[16:31], v[156:159], v[32:35], v[16:31]
	v_sub_f32_e32 v39, v39, v212
	v_exp_f32_e32 v39, v39
	v_sub_f32_e32 v40, v40, v212
	v_exp_f32_e32 v40, v40
	v_sub_f32_e32 v42, v42, v212
	v_add_f32_e32 v48, v38, v203
	v_exp_f32_e32 v42, v42
	s_waitcnt lgkmcnt(5)
; #define MFMA(a, b, c) __builtin_amdgcn_mfma_f32_32x32x16_bf16((a), (b), (c), 0, 0, 0)
; DI float fexp2(float x) { return __builtin_amdgcn_exp2f(x); }
; DI void phase_attn(const Params& p, int hf, bool skipctx, char* smem, int& rot) {
;     ...
;         bf16x8 kf[2][6];
; #pragma unroll
;         for (int kb = 0; kb < 2; ++kb)
; #pragma unroll
;           for (int ks = 0; ks < 6; ++ks) kf[kb][ks] = *(const bf16x8*)(sk + (kb * 32 + r) * KROW + (ks * 16 + h * 8) * 2);
;         __builtin_amdgcn_sched_barrier(0);
; #pragma unroll
;         for (int ks = 0; ks < 6; ++ks)
; #pragma unroll
;           for (int kb = 0; kb < 2; ++kb) st[kb] = MFMA(kf[kb][ks], qf[ks], st[kb]);
;         __builtin_amdgcn_sched_barrier(0);
;       }
;       bf16x8 vf[2][2][2];
; #pragma unroll
;       for (int kb = 0; kb < 2; ++kb)
; #pragma unroll
;         for (int s2 = 0; s2 < 2; ++s2)
; #pragma unroll
;           for (int dvb = 0; dvb < 2; ++dvb) {
;             const char* vp = sv + (dvb * 32 + r) * VROW + (kb * 32 + 16 * s2 + 4 * h) * 2;
;             const s16x4 lo = *(const s16x4*)vp, hi = *(const s16x4*)(vp + 16);
;             vf[kb][s2][dvb] = __builtin_shufflevector(lo, hi, 0, 1, 2, 3, 4, 5, 6, 7);
;           }
;       float mx = st[0][0];
; #pragma unroll
;       for (int i = 0; i < 16; ++i) { mx = fmaxf(mx, st[0][i]); mx = fmaxf(mx, st[1][i]); }
;       if (__any(mx > m_run + 8.f)) {
;         mx = fmaxf(mx, __shfl_xor(mx, 32));
;         const float m_new = fmaxf(m_run, mx);
;         const float alpha = fexp2(m_run - m_new);
;         m_run = m_new;
;         l_run *= alpha;
; #pragma unroll
;         for (int i = 0; i < 16; ++i) { o[0][i] *= alpha; o[1][i] *= alpha; }
;       }
;       float ps = 0.f;
; #pragma unroll
;       for (int kb = 0; kb < 2; ++kb)
; #pragma unroll
;         for (int i = 0; i < 16; ++i) { const float e = fexp2(st[kb][i] - m_run); st[kb][i] = e; ps += e; }
;       l_run += ps;
; #pragma unroll
;       for (int kb = 0; kb < 2; ++kb)
; #pragma unroll
;         for (int s2 = 0; s2 < 2; ++s2) {
;           const bf16x8 pb = pack8(st[kb][8 * s2 + 0], st[kb][8 * s2 + 1], st[kb][8 * s2 + 2], st[kb][8 * s2 + 3], st[kb][8 * s2 + 4], st[kb][8 * s2 + 5], st[kb][8 * s2 + 6], st[kb][8 * s2 + 7]);
; #pragma unroll
;           for (int dvb = 0; dvb < 2; ++dvb) o[dvb] = MFMA(vf[kb][s2][dvb], pb, o[dvb]);
	v_mfma_f32_32x32x16_bf16 v[0:15], v[152:155], v[32:35], v[0:15]
	v_sub_f32_e32 v32, v41, v212
	v_exp_f32_e32 v41, v32
	v_cvt_pk_bf16_f32 v32, v56, v57
	v_cvt_pk_bf16_f32 v33, v58, v59
	v_cvt_pk_bf16_f32 v34, v60, v61
	v_cvt_pk_bf16_f32 v35, v62, v63
	v_sub_f32_e32 v43, v43, v212
	v_add_f32_e32 v48, v39, v48
	v_mfma_f32_32x32x16_bf16 v[16:31], v[148:151], v[32:35], v[16:31]
	v_exp_f32_e32 v43, v43
	v_sub_f32_e32 v44, v44, v212
	v_add_f32_e32 v48, v40, v48
	v_exp_f32_e32 v44, v44
	v_add_f32_e32 v48, v41, v48
	s_waitcnt lgkmcnt(4)
	v_mfma_f32_32x32x16_bf16 v[0:15], v[144:147], v[32:35], v[0:15]
	v_add_f32_e32 v32, v42, v48
	v_add_f32_e32 v32, v43, v32
	v_add_f32_e32 v48, v44, v32
	v_cvt_pk_bf16_f32 v32, v200, v201
	v_cvt_pk_bf16_f32 v33, v195, v202
	v_cvt_pk_bf16_f32 v34, v36, v37
	v_cvt_pk_bf16_f32 v35, v38, v39
	v_sub_f32_e32 v36, v45, v212
	v_exp_f32_e32 v36, v36
	s_waitcnt lgkmcnt(3)
	v_mfma_f32_32x32x16_bf16 v[16:31], v[140:143], v[32:35], v[16:31]
	v_sub_f32_e32 v37, v46, v212
	v_exp_f32_e32 v37, v37
	v_sub_f32_e32 v38, v47, v212
	v_exp_f32_e32 v38, v38
	v_add_f32_e32 v39, v36, v48
	s_waitcnt lgkmcnt(2)
	v_mfma_f32_32x32x16_bf16 v[0:15], v[136:139], v[32:35], v[0:15]
	v_add_f32_e32 v32, v37, v39
	v_add_f32_e32 v32, v38, v32
	v_add_f32_e32 v213, v213, v32
	v_cvt_pk_bf16_f32 v32, v40, v41
	v_cvt_pk_bf16_f32 v33, v42, v43
	v_cvt_pk_bf16_f32 v34, v44, v36
	v_cvt_pk_bf16_f32 v35, v37, v38
	s_waitcnt lgkmcnt(1)
	s_nop 0
	v_mfma_f32_32x32x16_bf16 v[16:31], v[132:135], v[32:35], v[16:31]
	ds_read_b128 v[36:39], v190 offset:13312
	ds_read_b128 v[132:135], v190 offset:13344
	ds_read_b128 v[136:139], v190 offset:13376
	ds_read_b128 v[140:143], v190 offset:13408
	ds_read_b128 v[144:147], v190 offset:13440
	ds_read_b128 v[148:151], v190 offset:13472
	ds_read_b128 v[40:43], v190 offset:19968
	ds_read_b128 v[152:155], v190 offset:20000
	ds_read_b128 v[156:159], v190 offset:20032
	ds_read_b128 v[234:237], v190 offset:20064
	ds_read_b128 v[238:241], v190 offset:20096
	ds_read_b128 v[242:245], v190 offset:20128
	s_waitcnt lgkmcnt(12)
	v_mfma_f32_32x32x16_bf16 v[0:15], v[128:131], v[32:35], v[0:15]
	s_waitcnt lgkmcnt(11)
	v_mfma_f32_32x32x16_bf16 v[48:63], v[36:39], v[64:67], 0
	s_waitcnt lgkmcnt(5)
	v_mfma_f32_32x32x16_bf16 v[32:47], v[40:43], v[64:67], 0
	v_mfma_f32_32x32x16_bf16 v[48:63], v[132:135], v[68:71], v[48:63]
	s_waitcnt lgkmcnt(4)
	v_mfma_f32_32x32x16_bf16 v[32:47], v[152:155], v[68:71], v[32:47]
	v_mfma_f32_32x32x16_bf16 v[48:63], v[136:139], v[72:75], v[48:63]
	s_waitcnt lgkmcnt(3)
	v_mfma_f32_32x32x16_bf16 v[32:47], v[156:159], v[72:75], v[32:47]
	v_mfma_f32_32x32x16_bf16 v[48:63], v[140:143], v[88:91], v[48:63]
	s_waitcnt lgkmcnt(2)
	v_mfma_f32_32x32x16_bf16 v[32:47], v[234:237], v[88:91], v[32:47]
	v_mfma_f32_32x32x16_bf16 v[48:63], v[144:147], v[96:99], v[48:63]
	s_waitcnt lgkmcnt(1)
	v_mfma_f32_32x32x16_bf16 v[32:47], v[238:241], v[96:99], v[32:47]
	v_mfma_f32_32x32x16_bf16 v[48:63], v[148:151], v[100:103], v[48:63]
	s_waitcnt lgkmcnt(0)
	v_mfma_f32_32x32x16_bf16 v[32:47], v[242:245], v[100:103], v[32:47]
	s_nop 3
	ds_read_b128 v[156:159], v191 offset:128
	ds_read_b128 v[148:151], v191 offset:160
	ds_read_b128 v[152:155], v191 offset:8832
	ds_read_b128 v[144:147], v191 offset:8864
	ds_read_b128 v[140:143], v191 offset:192
	ds_read_b128 v[136:139], v191 offset:8896
	ds_read_b128 v[128:131], v191 offset:224
	ds_read_b128 v[132:135], v191 offset:8928
	v_max_f32_e32 v195, v32, v32
	v_max_f32_e32 v200, v48, v48
	v_max_f32_e32 v195, v200, v195
	v_max3_f32 v195, v195, v49, v33
	v_max3_f32 v195, v195, v50, v34
	v_max3_f32 v195, v195, v51, v35
	v_max3_f32 v195, v195, v52, v36
	v_max3_f32 v195, v195, v53, v37
	v_max3_f32 v195, v195, v54, v38
	v_max3_f32 v195, v195, v55, v39
	v_max3_f32 v195, v195, v56, v40
	v_max3_f32 v195, v195, v57, v41
	v_max3_f32 v195, v195, v58, v42
	v_max3_f32 v195, v195, v59, v43
	v_max3_f32 v195, v195, v60, v44
	v_max3_f32 v195, v195, v61, v45
	v_max3_f32 v195, v195, v62, v46
	v_max3_f32 v214, v195, v63, v47
	v_cmp_gt_f32_e32 vcc, v214, v216
	s_cbranch_vccz .LBB0_801
	v_cmp_lt_i32_e32 vcc, v224, v207
	s_nop 1
	v_cndmask_b32_e32 v195, v205, v224, vcc
	v_lshlrev_b32_e32 v195, 2, v195
	ds_bpermute_b32 v195, v195, v214
	s_waitcnt lgkmcnt(0)
	v_max3_f32 v195, v212, v214, v195
	v_sub_f32_e32 v200, v212, v195
	v_exp_f32_e32 v200, v200
	v_mov_b32_e32 v212, v195
	v_mul_f32_e32 v213, v213, v200
	v_pk_mul_f32 v[30:31], v[30:31], v[200:201] op_sel_hi:[1,0]
	v_pk_mul_f32 v[28:29], v[28:29], v[200:201] op_sel_hi:[1,0]
	v_pk_mul_f32 v[26:27], v[26:27], v[200:201] op_sel_hi:[1,0]
	v_pk_mul_f32 v[24:25], v[24:25], v[200:201] op_sel_hi:[1,0]
	v_pk_mul_f32 v[22:23], v[22:23], v[200:201] op_sel_hi:[1,0]
	v_pk_mul_f32 v[20:21], v[20:21], v[200:201] op_sel_hi:[1,0]
	v_pk_mul_f32 v[18:19], v[18:19], v[200:201] op_sel_hi:[1,0]
	v_pk_mul_f32 v[16:17], v[16:17], v[200:201] op_sel_hi:[1,0]
	v_pk_mul_f32 v[14:15], v[14:15], v[200:201] op_sel_hi:[1,0]
	v_pk_mul_f32 v[12:13], v[12:13], v[200:201] op_sel_hi:[1,0]
	v_pk_mul_f32 v[10:11], v[10:11], v[200:201] op_sel_hi:[1,0]
	v_pk_mul_f32 v[8:9], v[8:9], v[200:201] op_sel_hi:[1,0]
	v_pk_mul_f32 v[6:7], v[6:7], v[200:201] op_sel_hi:[1,0]
	v_pk_mul_f32 v[4:5], v[4:5], v[200:201] op_sel_hi:[1,0]
	v_pk_mul_f32 v[2:3], v[2:3], v[200:201] op_sel_hi:[1,0]
	v_pk_mul_f32 v[0:1], v[0:1], v[200:201] op_sel_hi:[1,0]
; #define MFMA(a, b, c) __builtin_amdgcn_mfma_f32_32x32x16_bf16((a), (b), (c), 0, 0, 0)
; DI float fexp2(float x) { return __builtin_amdgcn_exp2f(x); }
; DI void phase_attn(const Params& p, int hf, bool skipctx, char* smem, int& rot) {
;     ...
;       float ps = 0.f;
; #pragma unroll
;       for (int kb = 0; kb < 2; ++kb)
; #pragma unroll
;         for (int i = 0; i < 16; ++i) { const float e = fexp2(st[kb][i] - m_run); st[kb][i] = e; ps += e; }
;       l_run += ps;
; #pragma unroll
;       for (int kb = 0; kb < 2; ++kb)
; #pragma unroll
;         for (int s2 = 0; s2 < 2; ++s2) {
;           const bf16x8 pb = pack8(st[kb][8 * s2 + 0], st[kb][8 * s2 + 1], st[kb][8 * s2 + 2], st[kb][8 * s2 + 3], st[kb][8 * s2 + 4], st[kb][8 * s2 + 5], st[kb][8 * s2 + 6], st[kb][8 * s2 + 7]);
; #pragma unroll
;           for (int dvb = 0; dvb < 2; ++dvb) o[dvb] = MFMA(vf[kb][s2][dvb], pb, o[dvb]);
;         }
;     ...
;       ATT_WRITE(bk0, bk1, bk2, bv0, bv1, 1);
;       __syncthreads();
;       if (kt + 3 < nkt) ATT_LOAD(bk0, bk1, bk2, bv0, bv1, kt + 3);
.LBB0_801:
	v_sub_f32_e32 v48, v48, v212
	v_sub_f32_e32 v49, v49, v212
	v_sub_f32_e32 v50, v50, v212
	v_sub_f32_e32 v51, v51, v212
	v_sub_f32_e32 v52, v52, v212
	v_sub_f32_e32 v53, v53, v212
	v_sub_f32_e32 v54, v54, v212
	v_sub_f32_e32 v55, v55, v212
	v_exp_f32_e32 v48, v48
	v_exp_f32_e32 v49, v49
	v_exp_f32_e32 v50, v50
	v_exp_f32_e32 v51, v51
	v_exp_f32_e32 v52, v52
	v_exp_f32_e32 v53, v53
	v_exp_f32_e32 v54, v54
	v_exp_f32_e32 v55, v55
	v_cvt_pk_bf16_f32 v214, v48, v49
	v_cvt_pk_bf16_f32 v215, v50, v51
	v_cvt_pk_bf16_f32 v216, v52, v53
	v_cvt_pk_bf16_f32 v217, v54, v55
	v_sub_f32_e32 v56, v56, v212
	v_sub_f32_e32 v57, v57, v212
	s_waitcnt lgkmcnt(7)
	v_mfma_f32_32x32x16_bf16 v[16:31], v[156:159], v[214:217], v[16:31]
	v_sub_f32_e32 v58, v58, v212
	v_sub_f32_e32 v59, v59, v212
	v_sub_f32_e32 v60, v60, v212
	v_sub_f32_e32 v61, v61, v212
	v_sub_f32_e32 v62, v62, v212
	v_sub_f32_e32 v63, v63, v212
	v_exp_f32_e32 v56, v56
	s_waitcnt lgkmcnt(5)
	v_mfma_f32_32x32x16_bf16 v[0:15], v[152:155], v[214:217], v[0:15]
	v_exp_f32_e32 v57, v57
	v_exp_f32_e32 v58, v58
	v_exp_f32_e32 v59, v59
	v_exp_f32_e32 v60, v60
	v_exp_f32_e32 v61, v61
	v_exp_f32_e32 v62, v62
	v_exp_f32_e32 v63, v63
	v_cvt_pk_bf16_f32 v152, v56, v57
	v_cvt_pk_bf16_f32 v153, v58, v59
	v_cvt_pk_bf16_f32 v154, v60, v61
	v_cvt_pk_bf16_f32 v155, v62, v63
	v_sub_f32_e32 v32, v32, v212
	v_sub_f32_e32 v33, v33, v212
	v_mfma_f32_32x32x16_bf16 v[16:31], v[148:151], v[152:155], v[16:31]
	v_sub_f32_e32 v34, v34, v212
	v_sub_f32_e32 v35, v35, v212
	v_sub_f32_e32 v36, v36, v212
	v_sub_f32_e32 v37, v37, v212
	v_sub_f32_e32 v38, v38, v212
	v_sub_f32_e32 v39, v39, v212
	v_exp_f32_e32 v32, v32
	s_waitcnt lgkmcnt(4)
	v_mfma_f32_32x32x16_bf16 v[0:15], v[144:147], v[152:155], v[0:15]
	v_exp_f32_e32 v33, v33
	v_exp_f32_e32 v34, v34
	v_exp_f32_e32 v35, v35
	v_exp_f32_e32 v36, v36
	v_exp_f32_e32 v37, v37
	v_exp_f32_e32 v38, v38
	v_exp_f32_e32 v39, v39
	v_cvt_pk_bf16_f32 v144, v32, v33
	v_cvt_pk_bf16_f32 v145, v34, v35
	v_cvt_pk_bf16_f32 v146, v36, v37
	v_cvt_pk_bf16_f32 v147, v38, v39
	v_sub_f32_e32 v40, v40, v212
	v_sub_f32_e32 v41, v41, v212
	s_waitcnt lgkmcnt(3)
	v_mfma_f32_32x32x16_bf16 v[16:31], v[140:143], v[144:147], v[16:31]
	v_sub_f32_e32 v42, v42, v212
	v_sub_f32_e32 v43, v43, v212
	v_sub_f32_e32 v44, v44, v212
	v_sub_f32_e32 v45, v45, v212
	v_sub_f32_e32 v46, v46, v212
	v_sub_f32_e32 v47, v47, v212
	v_exp_f32_e32 v40, v40
	s_waitcnt lgkmcnt(2)
	v_mfma_f32_32x32x16_bf16 v[0:15], v[136:139], v[144:147], v[0:15]
	v_exp_f32_e32 v41, v41
	v_exp_f32_e32 v42, v42
	v_exp_f32_e32 v43, v43
	v_exp_f32_e32 v44, v44
	v_exp_f32_e32 v45, v45
	v_exp_f32_e32 v46, v46
	v_exp_f32_e32 v47, v47
	v_cvt_pk_bf16_f32 v136, v40, v41
	v_cvt_pk_bf16_f32 v137, v42, v43
	v_cvt_pk_bf16_f32 v138, v44, v45
	v_cvt_pk_bf16_f32 v139, v46, v47
	s_add_i32 s4, s4, 3
	s_cmp_ge_u32 s4, s13
	s_waitcnt lgkmcnt(1)
	v_mfma_f32_32x32x16_bf16 v[16:31], v[128:131], v[136:139], v[16:31]
	s_waitcnt vmcnt(1)
	ds_write_b128 v176, v[112:115] offset:44032
	ds_write_b128 v177, v[108:111] offset:44032
	ds_write_b128 v178, v[116:119] offset:44032
	ds_write2_b64 v186, v[120:121], v[122:123] offset1:2
	s_waitcnt vmcnt(0)
	ds_write2_b64 v187, v[124:125], v[126:127] offset1:2
	s_waitcnt lgkmcnt(0)
	s_barrier
	v_mfma_f32_32x32x16_bf16 v[0:15], v[132:135], v[136:139], v[0:15]
	ds_read_b128 v[238:241], v190 offset:44032
	ds_read_b128 v[128:131], v190 offset:44064
	ds_read_b128 v[132:135], v190 offset:44096
	ds_read_b128 v[136:139], v190 offset:44128
	ds_read_b128 v[140:143], v190 offset:44160
	ds_read_b128 v[144:147], v190 offset:44192
	ds_read_b128 v[242:245], v190 offset:50688
	ds_read_b128 v[148:151], v190 offset:50720
	ds_read_b128 v[152:155], v190 offset:50752
	ds_read_b128 v[156:159], v190 offset:50784
	ds_read_b128 v[214:217], v190 offset:50816
	ds_read_b128 v[234:237], v190 offset:50848
	s_cbranch_scc1 .LBB0_803
	v_lshl_add_u64 v[108:109], s[94:95], 0, v[174:175]
	v_add_co_u32_e32 v108, vcc, 0x18b2e000, v108
	v_lshl_add_u64 v[110:111], s[94:95], 0, v[172:173]
	s_nop 0
	v_addc_co_u32_e32 v109, vcc, 0, v109, vcc
	v_add_co_u32_e32 v110, vcc, 0x18b2e000, v110
	v_lshl_add_u64 v[116:117], s[94:95], 0, v[170:171]
	s_nop 0
	v_addc_co_u32_e32 v111, vcc, 0, v111, vcc
	v_add_co_u32_e32 v116, vcc, 0x18b2e000, v116
	v_lshl_add_u64 v[120:121], s[94:95], 0, v[166:167]
	s_nop 0
	v_addc_co_u32_e32 v117, vcc, 0, v117, vcc
	v_lshl_add_u64 v[124:125], s[94:95], 0, v[168:169]
	global_load_dwordx4 v[112:115], v[108:109], off
	s_nop 0
	global_load_dwordx4 v[108:111], v[110:111], off
	s_nop 0
	global_load_dwordx4 v[116:119], v[116:117], off
	s_nop 0
	global_load_dwordx4 v[120:123], v[120:121], off
	s_nop 0
	global_load_dwordx4 v[124:127], v[124:125], off
; #define MFMA(a, b, c) __builtin_amdgcn_mfma_f32_32x32x16_bf16((a), (b), (c), 0, 0, 0)
; DI float fexp2(float x) { return __builtin_amdgcn_exp2f(x); }
; DI void phase_attn(const Params& p, int hf, bool skipctx, char* smem, int& rot) {
;     ...
;         bf16x8 kf[2][6];
; #pragma unroll
;         for (int kb = 0; kb < 2; ++kb)
; #pragma unroll
;           for (int ks = 0; ks < 6; ++ks) kf[kb][ks] = *(const bf16x8*)(sk + (kb * 32 + r) * KROW + (ks * 16 + h * 8) * 2);
;         __builtin_amdgcn_sched_barrier(0);
; #pragma unroll
;         for (int ks = 0; ks < 6; ++ks)
; #pragma unroll
;           for (int kb = 0; kb < 2; ++kb) st[kb] = MFMA(kf[kb][ks], qf[ks], st[kb]);
;         __builtin_amdgcn_sched_barrier(0);
;       }
;       bf16x8 vf[2][2][2];
; #pragma unroll
;       for (int kb = 0; kb < 2; ++kb)
; #pragma unroll
;         for (int s2 = 0; s2 < 2; ++s2)
; #pragma unroll
;           for (int dvb = 0; dvb < 2; ++dvb) {
;             const char* vp = sv + (dvb * 32 + r) * VROW + (kb * 32 + 16 * s2 + 4 * h) * 2;
;             const s16x4 lo = *(const s16x4*)vp, hi = *(const s16x4*)(vp + 16);
;             vf[kb][s2][dvb] = __builtin_shufflevector(lo, hi, 0, 1, 2, 3, 4, 5, 6, 7);
;           }
;       float mx = st[0][0];
; #pragma unroll
;       for (int i = 0; i < 16; ++i) { mx = fmaxf(mx, st[0][i]); mx = fmaxf(mx, st[1][i]); }
;       if (__any(mx > m_run + 8.f)) {
;         mx = fmaxf(mx, __shfl_xor(mx, 32));
;         const float m_new = fmaxf(m_run, mx);
;         const float alpha = fexp2(m_run - m_new);
;         m_run = m_new;
;         l_run *= alpha;
; #pragma unroll
;         for (int i = 0; i < 16; ++i) { o[0][i] *= alpha; o[1][i] *= alpha; }
;       }
.LBB0_803:
	v_add_f32_e32 v48, 0, v48
	v_add_f32_e32 v48, v49, v48
	v_add_f32_e32 v48, v50, v48
	v_add_f32_e32 v48, v51, v48
	v_add_f32_e32 v48, v52, v48
	v_add_f32_e32 v48, v53, v48
	v_add_f32_e32 v48, v54, v48
	v_add_f32_e32 v48, v55, v48
	v_add_f32_e32 v48, v56, v48
	v_add_f32_e32 v48, v57, v48
	v_add_f32_e32 v48, v58, v48
	v_add_f32_e32 v48, v59, v48
	v_add_f32_e32 v48, v60, v48
	v_add_f32_e32 v48, v61, v48
	v_add_f32_e32 v48, v62, v48
	v_add_f32_e32 v48, v63, v48
	v_add_f32_e32 v32, v32, v48
	v_add_f32_e32 v32, v33, v32
	v_add_f32_e32 v32, v34, v32
	v_add_f32_e32 v32, v35, v32
	v_add_f32_e32 v32, v36, v32
	v_add_f32_e32 v32, v37, v32
	v_add_f32_e32 v32, v38, v32
	v_add_f32_e32 v32, v39, v32
	v_add_f32_e32 v32, v40, v32
	v_add_f32_e32 v32, v41, v32
	v_add_f32_e32 v32, v42, v32
	v_add_f32_e32 v32, v43, v32
	v_add_f32_e32 v32, v44, v32
	v_add_f32_e32 v32, v45, v32
	v_add_f32_e32 v32, v46, v32
	v_add_f32_e32 v32, v47, v32
	v_add_f32_e32 v213, v213, v32
	s_waitcnt lgkmcnt(11)
	v_mfma_f32_32x32x16_bf16 v[48:63], v[238:241], v[64:67], 0
	s_waitcnt lgkmcnt(5)
	v_mfma_f32_32x32x16_bf16 v[32:47], v[242:245], v[64:67], 0
	v_mfma_f32_32x32x16_bf16 v[48:63], v[128:131], v[68:71], v[48:63]
	s_waitcnt lgkmcnt(4)
	v_mfma_f32_32x32x16_bf16 v[32:47], v[148:151], v[68:71], v[32:47]
	v_mfma_f32_32x32x16_bf16 v[48:63], v[132:135], v[72:75], v[48:63]
	s_waitcnt lgkmcnt(3)
	v_mfma_f32_32x32x16_bf16 v[32:47], v[152:155], v[72:75], v[32:47]
	v_mfma_f32_32x32x16_bf16 v[48:63], v[136:139], v[88:91], v[48:63]
	s_waitcnt lgkmcnt(2)
	v_mfma_f32_32x32x16_bf16 v[32:47], v[156:159], v[88:91], v[32:47]
	v_mfma_f32_32x32x16_bf16 v[48:63], v[140:143], v[96:99], v[48:63]
	s_waitcnt lgkmcnt(1)
	v_mfma_f32_32x32x16_bf16 v[32:47], v[214:217], v[96:99], v[32:47]
	v_mfma_f32_32x32x16_bf16 v[48:63], v[144:147], v[100:103], v[48:63]
	s_waitcnt lgkmcnt(0)
	v_mfma_f32_32x32x16_bf16 v[32:47], v[234:237], v[100:103], v[32:47]
	s_nop 3
	ds_read_b128 v[152:155], v191 offset:52736
	ds_read_b128 v[156:159], v191 offset:44032
	ds_read_b128 v[148:151], v191 offset:44064
	ds_read_b128 v[144:147], v191 offset:52768
	ds_read_b128 v[140:143], v191 offset:44096
	ds_read_b128 v[136:139], v191 offset:52800
	ds_read_b128 v[132:135], v191 offset:44128
	ds_read_b128 v[128:131], v191 offset:52832
	v_max_f32_e32 v195, v32, v32
	v_max_f32_e32 v200, v48, v48
	v_max_f32_e32 v195, v200, v195
	v_max3_f32 v195, v195, v49, v33
	v_max3_f32 v195, v195, v50, v34
	v_max3_f32 v195, v195, v51, v35
	v_max3_f32 v195, v195, v52, v36
	v_max3_f32 v195, v195, v53, v37
	v_max3_f32 v195, v195, v54, v38
	v_max3_f32 v195, v195, v55, v39
	v_max3_f32 v195, v195, v56, v40
	v_max3_f32 v195, v195, v57, v41
	v_max3_f32 v195, v195, v58, v42
	v_max3_f32 v195, v195, v59, v43
	v_max3_f32 v195, v195, v60, v44
	v_max3_f32 v195, v195, v61, v45
	v_max3_f32 v195, v195, v62, v46
	v_max3_f32 v215, v195, v63, v47
	v_add_f32_e32 v214, 0x41000000, v212
	v_cmp_gt_f32_e32 vcc, v215, v214
	s_cbranch_vccz .LBB0_805
	v_cmp_lt_i32_e32 vcc, v224, v207
	s_nop 1
	v_cndmask_b32_e32 v195, v205, v224, vcc
	v_lshlrev_b32_e32 v195, 2, v195
	ds_bpermute_b32 v195, v195, v215
	s_waitcnt lgkmcnt(0)
	v_max3_f32 v195, v212, v215, v195
	v_sub_f32_e32 v200, v212, v195
	v_exp_f32_e32 v200, v200
	v_add_f32_e32 v214, 0x41000000, v195
	v_mov_b32_e32 v212, v195
	v_mul_f32_e32 v213, v213, v200
	v_pk_mul_f32 v[30:31], v[30:31], v[200:201] op_sel_hi:[1,0]
	v_pk_mul_f32 v[28:29], v[28:29], v[200:201] op_sel_hi:[1,0]
	v_pk_mul_f32 v[26:27], v[26:27], v[200:201] op_sel_hi:[1,0]
	v_pk_mul_f32 v[24:25], v[24:25], v[200:201] op_sel_hi:[1,0]
	v_pk_mul_f32 v[22:23], v[22:23], v[200:201] op_sel_hi:[1,0]
	v_pk_mul_f32 v[20:21], v[20:21], v[200:201] op_sel_hi:[1,0]
	v_pk_mul_f32 v[18:19], v[18:19], v[200:201] op_sel_hi:[1,0]
	v_pk_mul_f32 v[16:17], v[16:17], v[200:201] op_sel_hi:[1,0]
	v_pk_mul_f32 v[14:15], v[14:15], v[200:201] op_sel_hi:[1,0]
	v_pk_mul_f32 v[12:13], v[12:13], v[200:201] op_sel_hi:[1,0]
	v_pk_mul_f32 v[10:11], v[10:11], v[200:201] op_sel_hi:[1,0]
	v_pk_mul_f32 v[8:9], v[8:9], v[200:201] op_sel_hi:[1,0]
	v_pk_mul_f32 v[6:7], v[6:7], v[200:201] op_sel_hi:[1,0]
	v_pk_mul_f32 v[4:5], v[4:5], v[200:201] op_sel_hi:[1,0]
	v_pk_mul_f32 v[2:3], v[2:3], v[200:201] op_sel_hi:[1,0]
	v_pk_mul_f32 v[0:1], v[0:1], v[200:201] op_sel_hi:[1,0]
; #define MFMA(a, b, c) __builtin_amdgcn_mfma_f32_32x32x16_bf16((a), (b), (c), 0, 0, 0)
; DI float fexp2(float x) { return __builtin_amdgcn_exp2f(x); }
; DI void phase_attn(const Params& p, int hf, bool skipctx, char* smem, int& rot) {
;     ...
;         bf16x8 kf[2][6];
; #pragma unroll
;         for (int kb = 0; kb < 2; ++kb)
; #pragma unroll
;           for (int ks = 0; ks < 6; ++ks) kf[kb][ks] = *(const bf16x8*)(sk + (kb * 32 + r) * KROW + (ks * 16 + h * 8) * 2);
;         __builtin_amdgcn_sched_barrier(0);
; #pragma unroll
;         for (int ks = 0; ks < 6; ++ks)
; #pragma unroll
;           for (int kb = 0; kb < 2; ++kb) st[kb] = MFMA(kf[kb][ks], qf[ks], st[kb]);
;         __builtin_amdgcn_sched_barrier(0);
;       }
;       bf16x8 vf[2][2][2];
; #pragma unroll
;       for (int kb = 0; kb < 2; ++kb)
; #pragma unroll
;         for (int s2 = 0; s2 < 2; ++s2)
; #pragma unroll
;           for (int dvb = 0; dvb < 2; ++dvb) {
;             const char* vp = sv + (dvb * 32 + r) * VROW + (kb * 32 + 16 * s2 + 4 * h) * 2;
;             const s16x4 lo = *(const s16x4*)vp, hi = *(const s16x4*)(vp + 16);
;             vf[kb][s2][dvb] = __builtin_shufflevector(lo, hi, 0, 1, 2, 3, 4, 5, 6, 7);
;           }
;       float mx = st[0][0];
; #pragma unroll
;       for (int i = 0; i < 16; ++i) { mx = fmaxf(mx, st[0][i]); mx = fmaxf(mx, st[1][i]); }
;       if (__any(mx > m_run + 8.f)) {
;         mx = fmaxf(mx, __shfl_xor(mx, 32));
;         const float m_new = fmaxf(m_run, mx);
;         const float alpha = fexp2(m_run - m_new);
;         m_run = m_new;
;         l_run *= alpha;
; #pragma unroll
;         for (int i = 0; i < 16; ++i) { o[0][i] *= alpha; o[1][i] *= alpha; }
;       }
;       float ps = 0.f;
; #pragma unroll
;       for (int kb = 0; kb < 2; ++kb)
; #pragma unroll
;         for (int i = 0; i < 16; ++i) { const float e = fexp2(st[kb][i] - m_run); st[kb][i] = e; ps += e; }
;       l_run += ps;
; #pragma unroll
;       for (int kb = 0; kb < 2; ++kb)
; #pragma unroll
;         for (int s2 = 0; s2 < 2; ++s2) {
;           const bf16x8 pb = pack8(st[kb][8 * s2 + 0], st[kb][8 * s2 + 1], st[kb][8 * s2 + 2], st[kb][8 * s2 + 3], st[kb][8 * s2 + 4], st[kb][8 * s2 + 5], st[kb][8 * s2 + 6], st[kb][8 * s2 + 7]);
; #pragma unroll
;           for (int dvb = 0; dvb < 2; ++dvb) o[dvb] = MFMA(vf[kb][s2][dvb], pb, o[dvb]);
.LBB0_805:
	v_sub_f32_e32 v48, v48, v212
	v_exp_f32_e32 v48, v48
	v_sub_f32_e32 v49, v49, v212
	v_exp_f32_e32 v49, v49
	v_sub_f32_e32 v50, v50, v212
	v_exp_f32_e32 v50, v50
	v_sub_f32_e32 v51, v51, v212
	v_exp_f32_e32 v51, v51
	v_sub_f32_e32 v52, v52, v212
	v_add_f32_e32 v195, 0, v48
	v_exp_f32_e32 v52, v52
	v_sub_f32_e32 v53, v53, v212
	v_add_f32_e32 v195, v49, v195
	v_exp_f32_e32 v53, v53
	v_sub_f32_e32 v54, v54, v212
	v_add_f32_e32 v195, v50, v195
	v_exp_f32_e32 v54, v54
	v_sub_f32_e32 v55, v55, v212
	v_add_f32_e32 v195, v51, v195
	v_exp_f32_e32 v55, v55
	v_sub_f32_e32 v56, v56, v212
	v_add_f32_e32 v195, v52, v195
	v_exp_f32_e32 v56, v56
	v_sub_f32_e32 v57, v57, v212
	v_add_f32_e32 v195, v53, v195
	v_exp_f32_e32 v57, v57
	v_sub_f32_e32 v58, v58, v212
	v_add_f32_e32 v195, v54, v195
	v_exp_f32_e32 v58, v58
	v_sub_f32_e32 v59, v59, v212
	v_add_f32_e32 v195, v55, v195
	v_exp_f32_e32 v59, v59
	v_sub_f32_e32 v60, v60, v212
	v_add_f32_e32 v195, v56, v195
	v_exp_f32_e32 v60, v60
	v_sub_f32_e32 v61, v61, v212
	v_add_f32_e32 v195, v57, v195
	v_exp_f32_e32 v61, v61
	v_sub_f32_e32 v62, v62, v212
	v_add_f32_e32 v195, v58, v195
	v_exp_f32_e32 v62, v62
	v_sub_f32_e32 v63, v63, v212
	v_add_f32_e32 v195, v59, v195
	v_exp_f32_e32 v63, v63
	v_sub_f32_e32 v32, v32, v212
	v_add_f32_e32 v195, v60, v195
	v_exp_f32_e32 v200, v32
	v_sub_f32_e32 v32, v33, v212
	v_add_f32_e32 v195, v61, v195
	v_exp_f32_e32 v201, v32
	v_sub_f32_e32 v33, v34, v212
	v_add_f32_e32 v32, v62, v195
	v_exp_f32_e32 v195, v33
	v_sub_f32_e32 v33, v35, v212
	v_add_f32_e32 v32, v63, v32
	v_exp_f32_e32 v202, v33
	v_sub_f32_e32 v33, v36, v212
	v_add_f32_e32 v32, v200, v32
	v_exp_f32_e32 v36, v33
	v_sub_f32_e32 v33, v37, v212
	v_add_f32_e32 v32, v201, v32
	v_exp_f32_e32 v37, v33
	v_add_f32_e32 v32, v195, v32
	v_add_f32_e32 v32, v202, v32
	v_add_f32_e32 v32, v36, v32
	v_add_f32_e32 v203, v37, v32
	v_cvt_pk_bf16_f32 v32, v48, v49
	v_cvt_pk_bf16_f32 v33, v50, v51
	v_cvt_pk_bf16_f32 v34, v52, v53
	v_cvt_pk_bf16_f32 v35, v54, v55
	v_sub_f32_e32 v38, v38, v212
	v_exp_f32_e32 v38, v38
	s_waitcnt lgkmcnt(6)
	v_mfma_f32_32x32x16_bf16 v[16:31], v[156:159], v[32:35], v[16:31]
	v_sub_f32_e32 v39, v39, v212
	v_exp_f32_e32 v39, v39
	v_sub_f32_e32 v40, v40, v212
	v_exp_f32_e32 v40, v40
	v_sub_f32_e32 v42, v42, v212
	v_add_f32_e32 v48, v38, v203
	v_exp_f32_e32 v42, v42
	v_mfma_f32_32x32x16_bf16 v[0:15], v[152:155], v[32:35], v[0:15]
	v_sub_f32_e32 v32, v41, v212
	v_exp_f32_e32 v41, v32
	v_cvt_pk_bf16_f32 v32, v56, v57
	v_cvt_pk_bf16_f32 v33, v58, v59
	v_cvt_pk_bf16_f32 v34, v60, v61
	v_cvt_pk_bf16_f32 v35, v62, v63
	v_sub_f32_e32 v43, v43, v212
	v_add_f32_e32 v48, v39, v48
	s_waitcnt lgkmcnt(5)
	v_mfma_f32_32x32x16_bf16 v[16:31], v[148:151], v[32:35], v[16:31]
	v_exp_f32_e32 v43, v43
	v_sub_f32_e32 v44, v44, v212
	v_add_f32_e32 v48, v40, v48
	v_exp_f32_e32 v44, v44
	v_add_f32_e32 v48, v41, v48
	s_waitcnt lgkmcnt(4)
	v_mfma_f32_32x32x16_bf16 v[0:15], v[144:147], v[32:35], v[0:15]
	v_add_f32_e32 v32, v42, v48
	v_add_f32_e32 v32, v43, v32
	v_add_f32_e32 v48, v44, v32
	v_cvt_pk_bf16_f32 v32, v200, v201
	v_cvt_pk_bf16_f32 v33, v195, v202
	v_cvt_pk_bf16_f32 v34, v36, v37
	v_cvt_pk_bf16_f32 v35, v38, v39
	v_sub_f32_e32 v36, v45, v212
	v_exp_f32_e32 v36, v36
	s_waitcnt lgkmcnt(3)
	v_mfma_f32_32x32x16_bf16 v[16:31], v[140:143], v[32:35], v[16:31]
	v_sub_f32_e32 v37, v46, v212
	v_exp_f32_e32 v37, v37
	v_sub_f32_e32 v38, v47, v212
	v_exp_f32_e32 v38, v38
	v_add_f32_e32 v39, v36, v48
	s_waitcnt lgkmcnt(2)
	v_mfma_f32_32x32x16_bf16 v[0:15], v[136:139], v[32:35], v[0:15]
	v_add_f32_e32 v32, v37, v39
	v_add_f32_e32 v32, v38, v32
	v_add_f32_e32 v213, v213, v32
	v_cvt_pk_bf16_f32 v32, v40, v41
	v_cvt_pk_bf16_f32 v33, v42, v43
	v_cvt_pk_bf16_f32 v34, v44, v36
	v_cvt_pk_bf16_f32 v35, v37, v38
	s_waitcnt lgkmcnt(1)
	s_nop 0
	v_mfma_f32_32x32x16_bf16 v[16:31], v[132:135], v[32:35], v[16:31]
	ds_read_b128 v[36:39], v190 offset:57344
	ds_read_b128 v[132:135], v190 offset:57376
	ds_read_b128 v[136:139], v190 offset:57408
	ds_read_b128 v[140:143], v190 offset:57440
	ds_read_b128 v[144:147], v190 offset:57472
	ds_read_b128 v[148:151], v190 offset:57504
	ds_read_b128 v[40:43], v190 offset:64000
	ds_read_b128 v[152:155], v190 offset:64032
	ds_read_b128 v[156:159], v190 offset:64064
	ds_read_b128 v[216:219], v190 offset:64096
	ds_read_b128 v[234:237], v190 offset:64128
	ds_read_b128 v[238:241], v190 offset:64160
	s_waitcnt lgkmcnt(12)
	v_mfma_f32_32x32x16_bf16 v[0:15], v[128:131], v[32:35], v[0:15]
	s_waitcnt lgkmcnt(11)
	v_mfma_f32_32x32x16_bf16 v[48:63], v[36:39], v[64:67], 0
	s_waitcnt lgkmcnt(5)
	v_mfma_f32_32x32x16_bf16 v[32:47], v[40:43], v[64:67], 0
	v_mfma_f32_32x32x16_bf16 v[48:63], v[132:135], v[68:71], v[48:63]
	s_waitcnt lgkmcnt(4)
	v_mfma_f32_32x32x16_bf16 v[32:47], v[152:155], v[68:71], v[32:47]
	v_mfma_f32_32x32x16_bf16 v[48:63], v[136:139], v[72:75], v[48:63]
	s_waitcnt lgkmcnt(3)
	v_mfma_f32_32x32x16_bf16 v[32:47], v[156:159], v[72:75], v[32:47]
	v_mfma_f32_32x32x16_bf16 v[48:63], v[140:143], v[88:91], v[48:63]
	s_waitcnt lgkmcnt(2)
	v_mfma_f32_32x32x16_bf16 v[32:47], v[216:219], v[88:91], v[32:47]
	v_mfma_f32_32x32x16_bf16 v[48:63], v[144:147], v[96:99], v[48:63]
	s_waitcnt lgkmcnt(1)
	v_mfma_f32_32x32x16_bf16 v[32:47], v[234:237], v[96:99], v[32:47]
	v_mfma_f32_32x32x16_bf16 v[48:63], v[148:151], v[100:103], v[48:63]
	s_waitcnt lgkmcnt(0)
	v_mfma_f32_32x32x16_bf16 v[32:47], v[238:241], v[100:103], v[32:47]
	s_nop 3
	ds_read_b128 v[152:155], v191 offset:52864
	ds_read_b128 v[156:159], v191 offset:44160
	ds_read_b128 v[148:151], v191 offset:44192
	ds_read_b128 v[144:147], v191 offset:52896
	ds_read_b128 v[140:143], v191 offset:44224
	ds_read_b128 v[136:139], v191 offset:52928
	ds_read_b128 v[132:135], v191 offset:44256
	ds_read_b128 v[128:131], v191 offset:52960
	v_max_f32_e32 v195, v32, v32
	v_max_f32_e32 v200, v48, v48
	v_max_f32_e32 v195, v200, v195
	v_max3_f32 v195, v195, v49, v33
	v_max3_f32 v195, v195, v50, v34
	v_max3_f32 v195, v195, v51, v35
	v_max3_f32 v195, v195, v52, v36
	v_max3_f32 v195, v195, v53, v37
	v_max3_f32 v195, v195, v54, v38
	v_max3_f32 v195, v195, v55, v39
	v_max3_f32 v195, v195, v56, v40
	v_max3_f32 v195, v195, v57, v41
	v_max3_f32 v195, v195, v58, v42
	v_max3_f32 v195, v195, v59, v43
	v_max3_f32 v195, v195, v60, v44
	v_max3_f32 v195, v195, v61, v45
	v_max3_f32 v195, v195, v62, v46
	v_max3_f32 v215, v195, v63, v47
	v_cmp_gt_f32_e32 vcc, v215, v214
	s_cbranch_vccz .LBB0_807
; #define MFMA(a, b, c) __builtin_amdgcn_mfma_f32_32x32x16_bf16((a), (b), (c), 0, 0, 0)
; DI float fexp2(float x) { return __builtin_amdgcn_exp2f(x); }
; DI void phase_attn(const Params& p, int hf, bool skipctx, char* smem, int& rot) {
;     ...
;       if (__any(mx > m_run + 8.f)) {
;         mx = fmaxf(mx, __shfl_xor(mx, 32));
;         const float m_new = fmaxf(m_run, mx);
;         const float alpha = fexp2(m_run - m_new);
;         m_run = m_new;
;         l_run *= alpha;
; #pragma unroll
;         for (int i = 0; i < 16; ++i) { o[0][i] *= alpha; o[1][i] *= alpha; }
;       }
;       float ps = 0.f;
; #pragma unroll
;       for (int kb = 0; kb < 2; ++kb)
; #pragma unroll
;         for (int i = 0; i < 16; ++i) { const float e = fexp2(st[kb][i] - m_run); st[kb][i] = e; ps += e; }
;       l_run += ps;
; #pragma unroll
;       for (int kb = 0; kb < 2; ++kb)
; #pragma unroll
;         for (int s2 = 0; s2 < 2; ++s2) {
;           const bf16x8 pb = pack8(st[kb][8 * s2 + 0], st[kb][8 * s2 + 1], st[kb][8 * s2 + 2], st[kb][8 * s2 + 3], st[kb][8 * s2 + 4], st[kb][8 * s2 + 5], st[kb][8 * s2 + 6], st[kb][8 * s2 + 7]);
; #pragma unroll
;           for (int dvb = 0; dvb < 2; ++dvb) o[dvb] = MFMA(vf[kb][s2][dvb], pb, o[dvb]);
;         }
;     };
;     __syncthreads();
;     ATT_LOAD(ak0, ak1, ak2, av0, av1, 0);
;     ATT_LOAD(bk0, bk1, bk2, bv0, bv1, 1);
;     ATT_WRITE(ak0, ak1, ak2, av0, av1, 0);
;     __syncthreads();
;     for (int kt = 0; kt < nkt; kt += 2) {
;       if (kt + 2 < nkt) ATT_LOAD(ak0, ak1, ak2, av0, av1, kt + 2);
;       compute(0, 0); compute(0, 1);
;       ATT_WRITE(bk0, bk1, bk2, bv0, bv1, 1);
;       __syncthreads();
;       if (kt + 3 < nkt) ATT_LOAD(bk0, bk1, bk2, bv0, bv1, kt + 3);
;       compute(1, 0); compute(1, 1);
;       if (kt + 2 < nkt) ATT_WRITE(ak0, ak1, ak2, av0, av1, 0);
	v_cmp_lt_i32_e32 vcc, v224, v207
	s_nop 1
	v_cndmask_b32_e32 v195, v205, v224, vcc
	v_lshlrev_b32_e32 v195, 2, v195
	ds_bpermute_b32 v195, v195, v215
	s_waitcnt lgkmcnt(0)
	v_max3_f32 v195, v212, v215, v195
	v_sub_f32_e32 v200, v212, v195
	v_exp_f32_e32 v200, v200
	v_mov_b32_e32 v212, v195
	v_mul_f32_e32 v213, v213, v200
	v_pk_mul_f32 v[30:31], v[30:31], v[200:201] op_sel_hi:[1,0]
	v_pk_mul_f32 v[28:29], v[28:29], v[200:201] op_sel_hi:[1,0]
	v_pk_mul_f32 v[26:27], v[26:27], v[200:201] op_sel_hi:[1,0]
	v_pk_mul_f32 v[24:25], v[24:25], v[200:201] op_sel_hi:[1,0]
	v_pk_mul_f32 v[22:23], v[22:23], v[200:201] op_sel_hi:[1,0]
	v_pk_mul_f32 v[20:21], v[20:21], v[200:201] op_sel_hi:[1,0]
	v_pk_mul_f32 v[18:19], v[18:19], v[200:201] op_sel_hi:[1,0]
	v_pk_mul_f32 v[16:17], v[16:17], v[200:201] op_sel_hi:[1,0]
	v_pk_mul_f32 v[14:15], v[14:15], v[200:201] op_sel_hi:[1,0]
	v_pk_mul_f32 v[12:13], v[12:13], v[200:201] op_sel_hi:[1,0]
	v_pk_mul_f32 v[10:11], v[10:11], v[200:201] op_sel_hi:[1,0]
	v_pk_mul_f32 v[8:9], v[8:9], v[200:201] op_sel_hi:[1,0]
	v_pk_mul_f32 v[6:7], v[6:7], v[200:201] op_sel_hi:[1,0]
	v_pk_mul_f32 v[4:5], v[4:5], v[200:201] op_sel_hi:[1,0]
	v_pk_mul_f32 v[2:3], v[2:3], v[200:201] op_sel_hi:[1,0]
	v_pk_mul_f32 v[0:1], v[0:1], v[200:201] op_sel_hi:[1,0]
.LBB0_807:
	v_sub_f32_e32 v48, v48, v212
	v_sub_f32_e32 v49, v49, v212
	v_sub_f32_e32 v50, v50, v212
	v_sub_f32_e32 v51, v51, v212
	v_sub_f32_e32 v52, v52, v212
	v_sub_f32_e32 v53, v53, v212
	v_sub_f32_e32 v54, v54, v212
	v_sub_f32_e32 v55, v55, v212
	v_exp_f32_e32 v48, v48
	v_exp_f32_e32 v49, v49
	v_exp_f32_e32 v50, v50
	v_exp_f32_e32 v51, v51
	v_exp_f32_e32 v52, v52
	v_exp_f32_e32 v53, v53
	v_exp_f32_e32 v54, v54
	v_exp_f32_e32 v55, v55
	v_cvt_pk_bf16_f32 v214, v48, v49
	v_cvt_pk_bf16_f32 v215, v50, v51
	v_cvt_pk_bf16_f32 v216, v52, v53
	v_cvt_pk_bf16_f32 v217, v54, v55
	v_sub_f32_e32 v56, v56, v212
	v_sub_f32_e32 v57, v57, v212
	s_waitcnt lgkmcnt(6)
	v_mfma_f32_32x32x16_bf16 v[16:31], v[156:159], v[214:217], v[16:31]
	v_sub_f32_e32 v58, v58, v212
	v_sub_f32_e32 v59, v59, v212
	v_sub_f32_e32 v60, v60, v212
	v_sub_f32_e32 v61, v61, v212
	v_sub_f32_e32 v62, v62, v212
	v_sub_f32_e32 v63, v63, v212
	v_exp_f32_e32 v56, v56
	v_mfma_f32_32x32x16_bf16 v[0:15], v[152:155], v[214:217], v[0:15]
	v_exp_f32_e32 v57, v57
	v_exp_f32_e32 v58, v58
	v_exp_f32_e32 v59, v59
	v_exp_f32_e32 v60, v60
	v_exp_f32_e32 v61, v61
	v_exp_f32_e32 v62, v62
	v_exp_f32_e32 v63, v63
	v_cvt_pk_bf16_f32 v152, v56, v57
	v_cvt_pk_bf16_f32 v153, v58, v59
	v_cvt_pk_bf16_f32 v154, v60, v61
	v_cvt_pk_bf16_f32 v155, v62, v63
	v_sub_f32_e32 v32, v32, v212
	v_sub_f32_e32 v33, v33, v212
	s_waitcnt lgkmcnt(5)
	v_mfma_f32_32x32x16_bf16 v[16:31], v[148:151], v[152:155], v[16:31]
	v_sub_f32_e32 v34, v34, v212
	v_sub_f32_e32 v35, v35, v212
	v_sub_f32_e32 v36, v36, v212
	v_sub_f32_e32 v37, v37, v212
	v_sub_f32_e32 v38, v38, v212
	v_sub_f32_e32 v39, v39, v212
	v_exp_f32_e32 v32, v32
	s_waitcnt lgkmcnt(4)
	v_mfma_f32_32x32x16_bf16 v[0:15], v[144:147], v[152:155], v[0:15]
	v_exp_f32_e32 v33, v33
	v_exp_f32_e32 v34, v34
	v_exp_f32_e32 v35, v35
	v_exp_f32_e32 v36, v36
	v_exp_f32_e32 v37, v37
	v_exp_f32_e32 v38, v38
	v_exp_f32_e32 v39, v39
	v_cvt_pk_bf16_f32 v144, v32, v33
	v_cvt_pk_bf16_f32 v145, v34, v35
	v_cvt_pk_bf16_f32 v146, v36, v37
	v_cvt_pk_bf16_f32 v147, v38, v39
	v_sub_f32_e32 v40, v40, v212
	v_sub_f32_e32 v41, v41, v212
	s_waitcnt lgkmcnt(3)
	v_mfma_f32_32x32x16_bf16 v[16:31], v[140:143], v[144:147], v[16:31]
	v_sub_f32_e32 v42, v42, v212
	v_sub_f32_e32 v43, v43, v212
	v_sub_f32_e32 v44, v44, v212
	v_sub_f32_e32 v45, v45, v212
	v_sub_f32_e32 v46, v46, v212
	v_sub_f32_e32 v47, v47, v212
	v_exp_f32_e32 v40, v40
	s_waitcnt lgkmcnt(2)
	v_mfma_f32_32x32x16_bf16 v[0:15], v[136:139], v[144:147], v[0:15]
	v_exp_f32_e32 v41, v41
	v_exp_f32_e32 v42, v42
	v_exp_f32_e32 v43, v43
	v_exp_f32_e32 v44, v44
	v_exp_f32_e32 v45, v45
	v_exp_f32_e32 v46, v46
	v_exp_f32_e32 v47, v47
	v_cvt_pk_bf16_f32 v136, v40, v41
	v_cvt_pk_bf16_f32 v137, v42, v43
	v_cvt_pk_bf16_f32 v138, v44, v45
	v_cvt_pk_bf16_f32 v139, v46, v47
	s_andn2_b64 vcc, exec, s[36:37]
	s_waitcnt lgkmcnt(1)
	v_mfma_f32_32x32x16_bf16 v[16:31], v[132:135], v[136:139], v[16:31]
	s_waitcnt lgkmcnt(0)
	v_mfma_f32_32x32x16_bf16 v[0:15], v[128:131], v[136:139], v[0:15]
	s_cbranch_vccnz .LBB0_809
	ds_write_b128 v176, v[76:79]
	ds_write_b128 v177, v[80:83]
	ds_write_b128 v178, v[84:87]
	ds_write2_b64 v179, v[92:93], v[94:95] offset1:2
	ds_write2_b64 v180, v[104:105], v[106:107] offset1:2

; DI float bflo(unsigned u) { return __uint_as_float(u << 16); }
; DI float bfhi(unsigned u) { return __uint_as_float(u & 0xffff0000u); }
; DI f32x16 zero16() { f32x16 z; for (int i = 0; i < 16; ++i) z[i] = 0.f; return z; }
; DI void phase_attn(const Params& p, int hf, bool skipctx, char* smem, int& rot) {
;     ...
;       uint4 qu[6];
; #pragma unroll
;       for (int ks = 0; ks < 6; ++ks) qu[ks] = *(const uint4*)(Qb + tq * 768 + head * 96 + ks * 16 + h * 8);
; #pragma unroll
;       for (int ks = 0; ks < 4; ++ks) {
;         const uint4 u = qu[ks];
;         qf[ks] = pack8(bflo(u.x) * QSCALE, bfhi(u.x) * QSCALE, bflo(u.y) * QSCALE, bfhi(u.y) * QSCALE, bflo(u.z) * QSCALE, bfhi(u.z) * QSCALE, bflo(u.w) * QSCALE, bfhi(u.w) * QSCALE);
;       }
;       const unsigned a1[4] = {qu[4].x, qu[4].y, qu[4].z, qu[4].w}, a2[4] = {qu[5].x, qu[5].y, qu[5].z, qu[5].w};
;       float o1[8], o2[8];
;       const int sq_ = s0 + w * 32 + r;
; #pragma unroll
;       for (int e = 0; e < 8; ++e) {
;         const float x1 = ((e & 1) ? bfhi(a1[e >> 1]) : bflo(a1[e >> 1])) * QSCALE;
;         const float x2 = ((e & 1) ? bfhi(a2[e >> 1]) : bflo(a2[e >> 1])) * QSCALE;
;         float cs = 1.f, sn = 0.f;
;         if (sq_ >= LC) { cs = axc[(sq_ - LC) * 16 + 8 * h + e]; sn = axs[(sq_ - LC) * 16 + 8 * h + e]; }
;         o1[e] = x1 * cs - x2 * sn; o2[e] = x1 * sn + x2 * cs;
;       }
;       qf[4] = pack8(o1[0], o1[1], o1[2], o1[3], o1[4], o1[5], o1[6], o1[7]);
;       qf[5] = pack8(o2[0], o2[1], o2[2], o2[3], o2[4], o2[5], o2[6], o2[7]);
;     }
;     const bf16_t* Kg = Kb + (size_t)(bl * 8 + head) * S * 96;
;     const bf16_t* Vg = VTb + (size_t)(bl * 8 + head) * 64 * S;
;     f32x16 o[2]; o[0] = zero16(); o[1] = zero16();
;     float m_run = -1e30f, l_run = 0.f;
;     uint4 ak0, ak1, ak2, av0, av1, bk0, bk1, bk2, bv0, bv1;
;     const int kr0 = tid / 12, kc0 = tid - kr0 * 12, kr1 = (tid + 512) / 12, kc1 = (tid + 512) - kr1 * 12, kr2 = (tid + 1024) / 12, kc2 = (tid + 1024) - kr2 * 12;
.LBB0_1059:
	s_or_b64 exec, exec, s[26:27]
	s_waitcnt vmcnt(0)
	v_lshlrev_b32_e32 v27, 16, v23
	v_lshlrev_b32_e32 v26, 16, v19
	v_pk_mul_f32 v[26:27], v[26:27], s[48:49] op_sel_hi:[1,0]
	v_lshlrev_b32_e32 v47, 16, v22
	v_pk_mul_f32 v[28:29], v[26:27], v[30:31] op_sel:[0,1] op_sel_hi:[1,0]
	v_pk_mul_f32 v[26:27], v[26:27], v[30:31]
	v_and_b32_e32 v30, 0xffff0000, v19
	v_lshlrev_b32_e32 v46, 16, v18
	v_and_b32_e32 v19, 0xffff0000, v22
	v_and_b32_e32 v18, 0xffff0000, v18
	v_and_b32_e32 v31, 0xffff0000, v23
	v_pk_mul_f32 v[46:47], v[46:47], s[48:49] op_sel_hi:[1,0]
	v_pk_mul_f32 v[22:23], v[18:19], s[48:49] op_sel_hi:[1,0]
	v_pk_mul_f32 v[48:49], v[46:47], v[42:43] op_sel:[0,1] op_sel_hi:[1,0]
	v_pk_mul_f32 v[42:43], v[46:47], v[42:43]
	v_pk_mul_f32 v[18:19], v[22:23], v[40:41] op_sel:[0,1] op_sel_hi:[1,0]
	v_pk_mul_f32 v[22:23], v[22:23], v[40:41]
	v_mov_b32_e32 v40, v42
	v_mov_b32_e32 v41, v22
	v_mov_b32_e32 v22, v43
	v_pk_add_f32 v[22:23], v[40:41], v[22:23]
	v_lshlrev_b32_e32 v41, 16, v21
	v_lshlrev_b32_e32 v40, 16, v17
	v_pk_mul_f32 v[40:41], v[40:41], s[48:49] op_sel_hi:[1,0]
	v_mov_b32_e32 v46, v48
	v_mov_b32_e32 v47, v18
	v_mov_b32_e32 v18, v49
	v_pk_mul_f32 v[42:43], v[40:41], v[32:33] op_sel:[0,1] op_sel_hi:[1,0]
	v_pk_mul_f32 v[40:41], v[40:41], v[32:33]
	v_and_b32_e32 v33, 0xffff0000, v21
	v_and_b32_e32 v32, 0xffff0000, v17
	v_pk_add_f32 v[18:19], v[46:47], v[18:19] neg_lo:[0,1] neg_hi:[0,1]
	v_pk_mul_f32 v[46:47], v[32:33], s[48:49] op_sel_hi:[1,0]
	v_mov_b32_e32 v48, v42
	v_pk_mul_f32 v[32:33], v[46:47], v[34:35] op_sel:[0,1] op_sel_hi:[1,0]
	v_pk_mul_f32 v[34:35], v[46:47], v[34:35]
	v_mov_b32_e32 v49, v32
	v_mov_b32_e32 v32, v43
	v_mov_b32_e32 v42, v40
	v_mov_b32_e32 v43, v34
	v_mov_b32_e32 v34, v41
	v_lshlrev_b32_e32 v41, 16, v20
	v_lshlrev_b32_e32 v40, 16, v16
	v_and_b32_e32 v17, 0xffff0000, v20
	v_and_b32_e32 v16, 0xffff0000, v16
	v_pk_mul_f32 v[40:41], v[40:41], s[48:49] op_sel_hi:[1,0]
	v_pk_mul_f32 v[20:21], v[16:17], s[48:49] op_sel_hi:[1,0]
	v_pk_add_f32 v[34:35], v[42:43], v[34:35]
	v_pk_mul_f32 v[42:43], v[40:41], v[38:39] op_sel:[0,1] op_sel_hi:[1,0]
	v_pk_mul_f32 v[38:39], v[40:41], v[38:39]
	v_pk_mul_f32 v[16:17], v[20:21], v[36:37] op_sel:[0,1] op_sel_hi:[1,0]
	v_pk_mul_f32 v[20:21], v[20:21], v[36:37]
	v_mov_b32_e32 v36, v38
	v_mov_b32_e32 v37, v20
	v_mov_b32_e32 v20, v39
	v_pk_add_f32 v[20:21], v[36:37], v[20:21]
	v_lshlrev_b32_e32 v36, 16, v12
	v_and_b32_e32 v37, 0xffff0000, v12
	v_lshlrev_b32_e32 v12, 16, v13
	v_and_b32_e32 v13, 0xffff0000, v13
	v_pk_mul_f32 v[12:13], v[12:13], s[48:49] op_sel_hi:[1,0]
	v_lshlrev_b32_e32 v38, 16, v14
	v_cvt_pk_bf16_f32 v65, v12, v13
	v_lshlrev_b32_e32 v12, 16, v8
	v_and_b32_e32 v13, 0xffff0000, v8
	v_lshlrev_b32_e32 v8, 16, v9
	v_and_b32_e32 v9, 0xffff0000, v9
	v_pk_mul_f32 v[8:9], v[8:9], s[48:49] op_sel_hi:[1,0]
	v_and_b32_e32 v39, 0xffff0000, v14
	v_cvt_pk_bf16_f32 v69, v8, v9
	v_lshlrev_b32_e32 v8, 16, v4
	v_and_b32_e32 v9, 0xffff0000, v4
	v_lshlrev_b32_e32 v4, 16, v5
	v_and_b32_e32 v5, 0xffff0000, v5
	v_lshlrev_b32_e32 v14, 16, v15
	v_and_b32_e32 v15, 0xffff0000, v15
	v_pk_mul_f32 v[4:5], v[4:5], s[48:49] op_sel_hi:[1,0]
	s_mov_b32 s29, 0x2aaaaaab
	v_pk_mul_f32 v[14:15], v[14:15], s[48:49] op_sel_hi:[1,0]
	v_cvt_pk_bf16_f32 v73, v4, v5
	v_mul_hi_i32 v4, v160, s29
	v_cvt_pk_bf16_f32 v67, v14, v15
	v_lshlrev_b32_e32 v14, 16, v10
	v_and_b32_e32 v15, 0xffff0000, v10
	v_lshlrev_b32_e32 v10, 16, v11
	v_and_b32_e32 v11, 0xffff0000, v11
	v_lshrrev_b32_e32 v5, 31, v4
	v_ashrrev_i32_e32 v4, 1, v4
	v_pk_mul_f32 v[10:11], v[10:11], s[48:49] op_sel_hi:[1,0]
	v_add_u32_e32 v45, v4, v5
	v_cvt_pk_bf16_f32 v71, v10, v11
	v_lshlrev_b32_e32 v10, 16, v6
	v_and_b32_e32 v11, 0xffff0000, v6
	v_lshlrev_b32_e32 v6, 16, v7
	v_and_b32_e32 v7, 0xffff0000, v7
	v_mad_u64_u32 v[4:5], s[38:39], v45, -12, v[160:161]
	v_add_u32_e32 v164, 0x200, v160
	v_pk_mul_f32 v[6:7], v[6:7], s[48:49] op_sel_hi:[1,0]
	v_mul_hi_i32 v5, v164, s29
	v_cvt_pk_bf16_f32 v75, v6, v7
	v_lshrrev_b32_e32 v6, 31, v5
	v_ashrrev_i32_e32 v5, 1, v5
	s_mul_i32 s15, s4, 0xcc000
	v_add_u32_e32 v5, v5, v6
	v_pk_mul_f32 v[38:39], v[38:39], s[48:49] op_sel_hi:[1,0]
	v_pk_mul_f32 v[14:15], v[14:15], s[48:49] op_sel_hi:[1,0]
	s_mul_hi_i32 s5, s4, 0xcc000
	s_add_u32 s26, s90, s15
	v_mad_u64_u32 v[6:7], s[38:39], v5, -12, v[164:165]
	v_add_u32_e32 v162, 0x400, v160
	v_cvt_pk_bf16_f32 v66, v38, v39
	v_cvt_pk_bf16_f32 v70, v14, v15
	v_pk_mul_f32 v[8:9], v[8:9], s[48:49] op_sel_hi:[1,0]
	v_pk_mul_f32 v[10:11], v[10:11], s[48:49] op_sel_hi:[1,0]
	s_addc_u32 s27, s91, s5
	v_mul_hi_i32 v7, v162, s29
	v_lshlrev_b32_e32 v14, 3, v4
	v_lshlrev_b32_e32 v38, 3, v6
	v_pk_mul_f32 v[36:37], v[36:37], s[48:49] op_sel_hi:[1,0]
	v_pk_mul_f32 v[12:13], v[12:13], s[48:49] op_sel_hi:[1,0]
	v_cvt_pk_bf16_f32 v72, v8, v9
	v_cvt_pk_bf16_f32 v74, v10, v11
	v_lshrrev_b32_e32 v8, 31, v7
	v_ashrrev_i32_e32 v7, 1, v7
	v_mov_b64_e32 v[10:11], s[26:27]
	v_ashrrev_i32_e32 v15, 31, v14
	v_ashrrev_i32_e32 v39, 31, v38
	v_cvt_pk_bf16_f32 v64, v36, v37
	v_cvt_pk_bf16_f32 v68, v12, v13
	v_add_u32_e32 v7, v7, v8
	v_mad_i64_i32 v[12:13], s[26:27], v45, s17, v[10:11]
	v_lshlrev_b64 v[14:15], 1, v[14:15]
	v_mad_i64_i32 v[36:37], s[26:27], v5, s17, v[10:11]
	v_lshlrev_b64 v[38:39], 1, v[38:39]
	v_mad_u64_u32 v[8:9], s[38:39], v7, -12, v[162:163]
	v_lshl_add_u64 v[12:13], v[12:13], 0, v[14:15]
	v_lshl_add_u64 v[36:37], v[36:37], 0, v[38:39]
	s_barrier
; DI f32x16 zero16() { f32x16 z; for (int i = 0; i < 16; ++i) z[i] = 0.f; return z; }
; DI void phase_attn(const Params& p, int hf, bool skipctx, char* smem, int& rot) {
;     ...
;     const bf16_t* Kg = Kb + (size_t)(bl * 8 + head) * S * 96;
;     const bf16_t* Vg = VTb + (size_t)(bl * 8 + head) * 64 * S;
;     f32x16 o[2]; o[0] = zero16(); o[1] = zero16();
;     float m_run = -1e30f, l_run = 0.f;
;     uint4 ak0, ak1, ak2, av0, av1, bk0, bk1, bk2, bv0, bv1;
;     const int kr0 = tid / 12, kc0 = tid - kr0 * 12, kr1 = (tid + 512) / 12, kc1 = (tid + 512) - kr1 * 12, kr2 = (tid + 1024) / 12, kc2 = (tid + 1024) - kr2 * 12;
;     const int vr0 = tid >> 4, vr1 = (tid + 512) >> 4, vc = tid & 15;
;     ...
;     __syncthreads();
;     ATT_LOAD(ak0, ak1, ak2, av0, av1, 0);
;     ATT_LOAD(bk0, bk1, bk2, bv0, bv1, 1);
	global_load_dwordx4 v[76:79], v[12:13], off
	global_load_dwordx4 v[80:83], v[36:37], off
	v_lshlrev_b32_e32 v36, 3, v8
	s_mul_i32 s15, s4, 0x88000
	v_readlane_b32 s36, v252, 5
	v_ashrrev_i32_e32 v37, 31, v36
	s_mul_hi_i32 s5, s4, 0x88000
	v_readlane_b32 s37, v252, 6
	s_add_u32 s36, s36, s15
	v_mad_i64_i32 v[12:13], s[26:27], v7, s17, v[10:11]
	v_lshlrev_b64 v[36:37], 1, v[36:37]
	s_addc_u32 s37, s37, s5
	v_lshl_add_u64 v[12:13], v[12:13], 0, v[36:37]
	v_mov_b32_e32 v40, v42
	v_mov_b32_e32 v41, v16
	v_mov_b32_e32 v16, v43
	v_ashrrev_i32_e32 v9, 4, v160
	v_ashrrev_i32_e32 v50, 4, v164
	global_load_dwordx4 v[84:87], v[12:13], off
	v_mov_b64_e32 v[12:13], s[36:37]
	v_lshlrev_b32_e32 v165, 4, v160
	v_cvt_pk_bf16_f32 v100, v20, v21
	v_add_u32_e32 v20, 0x80, v5
	v_pk_add_f32 v[16:17], v[40:41], v[16:17] neg_lo:[0,1] neg_hi:[0,1]
	v_mad_i64_i32 v[40:41], s[26:27], v9, s16, v[12:13]
	v_and_b32_e32 v42, 0xf0, v165
	v_mov_b32_e32 v43, v221
	v_mad_i64_i32 v[12:13], s[26:27], v50, s16, v[12:13]
	v_cvt_pk_bf16_f32 v98, v18, v19
	v_cvt_pk_bf16_f32 v102, v22, v23
	v_add_u32_e32 v18, 0x80, v45
	v_mad_i64_i32 v[20:21], s[26:27], v20, s17, v[10:11]
	v_add_u32_e32 v22, 0x80, v7
	v_lshl_add_u64 v[40:41], v[40:41], 0, v[42:43]
	v_lshl_add_u64 v[12:13], v[12:13], 0, v[42:43]
	v_mad_i64_i32 v[18:19], s[26:27], v18, s17, v[10:11]
	v_lshl_add_u64 v[20:21], v[20:21], 0, v[38:39]
	v_mad_i64_i32 v[10:11], s[26:27], v22, s17, v[10:11]
	global_load_dwordx4 v[92:95], v[40:41], off
	global_load_dwordx4 v[104:107], v[12:13], off
	v_lshl_add_u64 v[18:19], v[18:19], 0, v[14:15]
	v_lshl_add_u64 v[10:11], v[10:11], 0, v[36:37]
	global_load_dwordx4 v[108:111], v[20:21], off
	global_load_dwordx4 v[116:119], v[10:11], off
	global_load_dwordx4 v[120:123], v[40:41], off offset:256
	global_load_dwordx4 v[112:115], v[18:19], off
	global_load_dwordx4 v[124:127], v[12:13], off offset:256
	v_lshlrev_b32_e32 v46, 16, v0
	v_and_b32_e32 v47, 0xffff0000, v0
	v_lshlrev_b32_e32 v0, 16, v1
	v_and_b32_e32 v1, 0xffff0000, v1
	v_pk_mul_f32 v[30:31], v[30:31], s[48:49] op_sel_hi:[1,0]
	v_pk_add_f32 v[32:33], v[48:49], v[32:33] neg_lo:[0,1] neg_hi:[0,1]
	v_pk_mul_f32 v[0:1], v[0:1], s[48:49] op_sel_hi:[1,0]
	v_lshlrev_b32_e32 v48, 16, v2
	v_and_b32_e32 v49, 0xffff0000, v2
	v_lshlrev_b32_e32 v2, 16, v3
	v_and_b32_e32 v3, 0xffff0000, v3
	v_pk_mul_f32 v[2:3], v[2:3], s[48:49] op_sel_hi:[1,0]
	v_cvt_pk_bf16_f32 v89, v0, v1
	v_pk_mul_f32 v[0:1], v[30:31], v[24:25] op_sel:[0,1] op_sel_hi:[1,0]
	v_cvt_pk_bf16_f32 v91, v2, v3
	v_mov_b32_e32 v2, v28
	v_mov_b32_e32 v3, v0
	v_mov_b32_e32 v0, v29
	v_pk_add_f32 v[0:1], v[2:3], v[0:1] neg_lo:[0,1] neg_hi:[0,1]
	v_pk_mul_f32 v[2:3], v[30:31], v[24:25]
	v_mul_lo_u32 v10, v45, s97
	v_mov_b32_e32 v24, v26
	v_mov_b32_e32 v25, v2
	v_mov_b32_e32 v2, v27
	v_add_u32_e32 v10, 0, v10
	v_lshlrev_b32_e32 v4, 4, v4
	v_pk_add_f32 v[2:3], v[24:25], v[2:3]
	v_add_u32_e32 v176, v10, v4
	v_mul_lo_u32 v4, v5, s97
	v_cvt_pk_bf16_f32 v103, v2, v3
	v_mad_i64_i32 v[2:3], s[26:27], v5, s17, 0
	v_add_u32_e32 v4, 0, v4
	v_lshlrev_b32_e32 v5, 4, v6
	v_cvt_pk_bf16_f32 v96, v16, v17
	v_cvt_pk_bf16_f32 v99, v0, v1
	v_mad_i64_i32 v[0:1], s[26:27], v45, s17, 0
	v_mad_i64_i32 v[16:17], s[26:27], v7, s17, 0
	v_add_u32_e32 v177, v4, v5
	v_mul_lo_u32 v4, v7, s97
	v_add_u32_e32 v4, 0, v4
	v_lshlrev_b32_e32 v5, 4, v8
	s_movk_i32 s26, 0x108
	v_add_u32_e32 v178, v4, v5
	v_mul_lo_u32 v4, v9, s26
	v_add_u32_e32 v5, 0, v4
	s_movk_i32 s27, 0x6800
	v_add3_u32 v179, v5, v42, s27
	v_mul_lo_u32 v5, v50, s26
	v_add_u32_e32 v6, 0, v5
	v_add3_u32 v180, v6, v42, s27
	v_or_b32_e32 v181, 32, v161
	v_or_b32_e32 v182, 64, v161
	v_or_b32_e32 v183, 0x60, v161
	v_readlane_b32 s27, v254, 35
	v_mul_u32_u24_e32 v19, 0x108, v44
	v_mad_u32_u24 v18, v44, s97, 0
	v_add_u32_e32 v21, s27, v4
	v_add_u32_e32 v22, s27, v5
	v_add_u32_e32 v23, s27, v161
	v_add_u32_e32 v24, s27, v181
	v_mov_b32_e32 v4, s27
	v_add_u32_e32 v25, s27, v182
	v_add_u32_e32 v26, s27, v183
	v_readlane_b32 s27, v254, 36
	v_mad_u32_u24 v184, v44, s26, v4
	v_add_u32_e32 v20, 0, v161
	v_mov_b32_e32 v4, s27
	v_mad_u32_u24 v185, v44, s26, v4
	s_add_u32 s26, s15, 0x1a49c300
	v_add_u32_e32 v27, s27, v161
	v_add_u32_e32 v28, s27, v181
	v_add_u32_e32 v29, s27, v182
	v_add_u32_e32 v30, s27, v183
	s_addc_u32 s27, s5, 0
	v_mov_b64_e32 v[4:5], s[26:27]
	v_mad_i64_i32 v[166:167], s[26:27], v9, s16, v[4:5]
	v_mad_i64_i32 v[168:169], s[26:27], v50, s16, v[4:5]
	v_mad_i64_i32 v[4:5], s[26:27], s4, v231, v[16:17]
	v_mad_i64_i32 v[2:3], s[26:27], s4, v231, v[2:3]
	v_mad_i64_i32 v[0:1], s[4:5], s4, v231, v[0:1]
	v_lshl_add_u64 v[174:175], v[0:1], 0, v[14:15]
	v_mov_b32_e32 v14, v221
	v_mov_b32_e32 v15, v221
	v_add_u32_e32 v186, v21, v42
	v_add_u32_e32 v187, v22, v42
	v_add_u32_e32 v188, v23, v19
	v_add_u32_e32 v16, v24, v19
	v_add_u32_e32 v17, v25, v19
	v_add_u32_e32 v21, v26, v19
	v_add_u32_e32 v22, v28, v19
	v_add_u32_e32 v23, v29, v19
	v_add_u32_e32 v24, v30, v19
	v_pk_mul_f32 v[46:47], v[46:47], s[48:49] op_sel_hi:[1,0]
	v_pk_mul_f32 v[48:49], v[48:49], s[48:49] op_sel_hi:[1,0]
	v_lshl_add_u64 v[170:171], v[4:5], 0, v[36:37]
	v_lshl_add_u64 v[172:173], v[2:3], 0, v[38:39]
	v_mov_b32_e32 v0, v221
	v_mov_b32_e32 v1, v221
	v_mov_b32_e32 v2, v221
	v_mov_b32_e32 v3, v221
	v_mov_b32_e32 v4, v221
	v_mov_b32_e32 v5, v221
	v_mov_b32_e32 v6, v221
	v_mov_b32_e32 v7, v221
	v_mov_b32_e32 v8, v221
	v_mov_b32_e32 v9, v221
	v_mov_b32_e32 v10, v221
	v_mov_b32_e32 v11, v221
	v_mov_b32_e32 v12, v221
	v_mov_b32_e32 v13, v221
	v_add_u32_e32 v189, v27, v19
	v_add_u32_e32 v190, v18, v220
	v_add_u32_e32 v191, v20, v19
	v_add_u32_e32 v194, 0x2000, v16
	v_add_u32_e32 v204, 0x2000, v17
	v_add_u32_e32 v206, 0x2000, v21
	v_add_u32_e32 v208, 0x2000, v22
	v_add_u32_e32 v210, 0x2000, v23
	v_add_u32_e32 v211, 0x2000, v24
	v_mov_b64_e32 v[30:31], v[14:15]
	v_cvt_pk_bf16_f32 v88, v46, v47
	v_cvt_pk_bf16_f32 v90, v48, v49
	v_cvt_pk_bf16_f32 v97, v32, v33
	v_cvt_pk_bf16_f32 v101, v34, v35
	v_or_b32_e32 v166, v166, v42
	v_or_b32_e32 v168, v168, v42
	s_mov_b32 s4, 0
	v_mov_b32_e32 v212, 0xf149f2ca
	v_mov_b32_e32 v213, 0
	v_mov_b64_e32 v[28:29], v[12:13]
	v_mov_b64_e32 v[26:27], v[10:11]
	v_mov_b64_e32 v[24:25], v[8:9]
	v_mov_b64_e32 v[22:23], v[6:7]
	v_mov_b64_e32 v[20:21], v[4:5]
	v_mov_b64_e32 v[18:19], v[2:3]
	v_mov_b64_e32 v[16:17], v[0:1]
	v_and_b32_e32 v200, 15, v192
	v_lshrrev_b32_e32 v201, 4, v192
	v_mul_u32_u24_e32 v179, 0x110, v201
	v_lshrrev_b32_e32 v202, 1, v200
	v_lshl_add_u32 v179, v202, 5, v179
	v_and_b32_e32 v202, 1, v200
	v_lshl_add_u32 v179, v202, 3, v179
	v_add_u32_e32 v179, 0x6800, v179
	v_add_u32_e32 v180, 0x2200, v179
	v_add_u32_e32 v186, 0xac00, v179
	v_add_u32_e32 v187, 0xac00, v180
	v_and_b32_e32 v200, 31, v192
	v_bfe_u32 v201, v192, 5, 1
	v_mul_u32_u24_e32 v191, 0x110, v200
	v_lshl_add_u32 v191, v201, 4, v191
	v_add_u32_e32 v191, 0x6800, v191
	s_waitcnt vmcnt(9)
; DI void phase_attn(const Params& p, int hf, bool skipctx, char* smem, int& rot) {
;     ...
;     ATT_WRITE(ak0, ak1, ak2, av0, av1, 0);
;     __syncthreads();
	ds_write_b128 v176, v[76:79]
	s_waitcnt vmcnt(8)
	ds_write_b128 v177, v[80:83]
	s_waitcnt vmcnt(7)
	ds_write_b128 v178, v[84:87]
	s_waitcnt vmcnt(6)
	ds_write2_b64 v179, v[92:93], v[94:95] offset1:2
	s_waitcnt vmcnt(5)
	ds_write2_b64 v180, v[104:105], v[106:107] offset1:2
	s_waitcnt lgkmcnt(0)
	s_barrier
